# attention QK cluster now carries V preload + next-tile prefetch in MFMA gaps; GEMM k-loops: counted vmcnt waits and prefetch address VALU/loads folded into MFMA clusters
# speedup vs baseline: 1.0264x; 1.0094x over previous
; DI int vblock() { int nb = gridDim.x, b = blockIdx.x; return ((nb & 7) == 0) ? (b & 7) * (nb >> 3) + (b >> 3) : b; }
; template <int BN>
; DI void gemm_main(f32x16 (&acc)[2][BN / 64], const GDesc& cur, const GDesc& nxt, GRegs<BN>& R, bool preloaded, char* smem) {
;     ...
;   const u16* ap = cur.A + (size_t)(cur.m0 + (tid >> 3)) * cur.lda + (tid & 7) * 8;
;   const u16* wp = cur.W + (size_t)(cur.n0 + (tid >> 3)) * cur.ldw + (tid & 7) * 8;
;   const u16* apn = nxt.A + (size_t)(nxt.m0 + (tid >> 3)) * nxt.lda + (tid & 7) * 8;
;   const u16* wpn = nxt.W + (size_t)(nxt.n0 + (tid >> 3)) * nxt.ldw + (tid & 7) * 8;
;   const int lda = cur.lda, ldw = cur.ldw, K = cur.K;
;   u16* asw = As + (tid >> 3) * 72 + (tid & 7) * 8;
;   u16* bsw = Bs + (tid >> 3) * 72 + (tid & 7) * 8;
;     ...
;   if (!preloaded) {
;     GM_LOAD(R.ra0, R.rb0, ap, wp, lda, ldw, 0)
;     GM_LOAD(R.ra1, R.rb1, ap, wp, lda, ldw, 64)
;   }
; DI void phase_gemm1(const Params& P, int layer, char* smem) {
;     ...
;   for (int job = vblock(); job < MT_TILES * 32; job += gridDim.x) {
;     int nt, mt; tile_map(job, 32, mt, nt);
;     int m0 = mt * 128, n0 = nt * 128;
;     f32x16 acc[2][2];
;     zero_acc<2>(acc);
;     { GRegs<128> R; const GDesc dc = gdesc(H, 1024, W, 1024, 1024, m0, n0); GDesc dn = dc; dn.valid = 0; gemm_main<128>(acc, dc, dn, R, false, smem); }
.LBB0_62:
	s_lshl_b32 s7, s7, 6
	s_sub_i32 s7, s4, s7
	s_ashr_i32 s11, s7, 3
	s_bfe_u32 s8, s4, 0x30003
	s_and_b32 s7, s11, 0x1fffff8
	v_mov_b32_e32 v18, v171
	s_lshl_b32 s10, s8, 7
	s_or_b32 s7, s7, s8
	s_lshl_b32 s8, s6, 7
	s_lshl_b32 s9, s7, 7
	v_ashrrev_i32_e32 v19, 3, v18
	v_add_u32_e32 v0, s8, v19
	v_ashrrev_i32_e32 v1, 31, v0
	v_readlane_b32 s6, v251, 2
	v_lshlrev_b64 v[0:1], 11, v[0:1]
	v_readlane_b32 s7, v251, 3
	v_lshlrev_b32_e32 v4, 4, v18
	s_waitcnt vmcnt(0)
	v_and_b32_e32 v168, 0x70, v4
	v_lshl_add_u64 v[2:3], s[6:7], 0, v[0:1]
	v_lshl_add_u64 v[2:3], v[2:3], 0, v[168:169]
	s_mov_b32 s12, 0x10000
	v_add_co_u32_e32 v6, vcc, s12, v2
	v_add_u32_e32 v4, s9, v19
	s_nop 0
	v_addc_co_u32_e32 v7, vcc, 0, v3, vcc
	s_mov_b32 s13, 0x20000
	v_ashrrev_i32_e32 v5, 31, v4
	v_readlane_b32 s6, v254, 22
	v_add_co_u32_e32 v8, vcc, s13, v2
	v_lshlrev_b64 v[4:5], 11, v[4:5]
	v_readlane_b32 s7, v254, 23
	v_addc_co_u32_e32 v9, vcc, 0, v3, vcc
	s_mov_b32 s14, 0x30000
	v_lshl_add_u64 v[4:5], s[6:7], 0, v[4:5]
	v_add_co_u32_e32 v10, vcc, s14, v2
	v_lshl_add_u64 v[4:5], v[4:5], 0, v[168:169]
	s_nop 0
	v_addc_co_u32_e32 v11, vcc, 0, v3, vcc
	v_add_co_u32_e32 v12, vcc, s12, v4
	v_mad_u64_u32 v[128:129], s[6:7], v19, s53, v[168:169]
	s_nop 0
	v_addc_co_u32_e32 v13, vcc, 0, v5, vcc
	v_add_co_u32_e32 v14, vcc, s13, v4
	s_lshl_b32 s6, s11, 7
	s_nop 0
	v_addc_co_u32_e32 v15, vcc, 0, v5, vcc
	v_add_co_u32_e32 v16, vcc, s14, v4
	s_and_b32 s6, s6, 0xfffffc00
	s_nop 0
	v_addc_co_u32_e32 v17, vcc, 0, v5, vcc
	global_load_dwordx4 v[64:67], v[2:3], off
	global_load_dwordx4 v[72:75], v[6:7], off
	global_load_dwordx4 v[80:83], v[8:9], off
	global_load_dwordx4 v[88:91], v[10:11], off
	global_load_dwordx4 v[96:99], v[4:5], off
	global_load_dwordx4 v[104:107], v[12:13], off
	global_load_dwordx4 v[112:115], v[14:15], off
	global_load_dwordx4 v[120:123], v[16:17], off
	global_load_dwordx4 v[68:71], v[2:3], off offset:128
	global_load_dwordx4 v[76:79], v[6:7], off offset:128
	global_load_dwordx4 v[84:87], v[8:9], off offset:128
	global_load_dwordx4 v[92:95], v[10:11], off offset:128
	global_load_dwordx4 v[100:103], v[4:5], off offset:128
	global_load_dwordx4 v[108:111], v[12:13], off offset:128
	global_load_dwordx4 v[116:119], v[14:15], off offset:128
	global_load_dwordx4 v[124:127], v[16:17], off offset:128
	v_and_b32_e32 v2, 31, v18
	v_lshrrev_b32_e32 v3, 1, v18
	v_and_or_b32 v2, v3, s54, v2
	v_mul_lo_u32 v5, v2, s53
	v_and_b32_e32 v2, 7, v18
	s_or_b32 s6, s10, s6
	v_and_b32_e32 v4, 16, v3
	v_and_b32_e32 v3, 0x5f, v18
	v_lshlrev_b32_e32 v168, 4, v2
	v_add_u32_e32 v2, s6, v19
	v_mul_u32_u24_e32 v6, 0x90, v3
	v_ashrrev_i32_e32 v3, 31, v2
	v_readlane_b32 s6, v254, 31
	v_lshlrev_b64 v[2:3], 11, v[2:3]
	v_readlane_b32 s7, v254, 32
	v_lshl_add_u64 v[132:133], s[76:77], 0, v[0:1]
	v_mov_b32_e32 v0, 0
	v_lshl_add_u64 v[130:131], s[6:7], 0, v[2:3]
	s_movk_i32 s10, 0xff80
	v_add_u32_e32 v129, v4, v5
	v_add_u32_e32 v138, v4, v6
	v_mov_b32_e32 v1, v0
	v_mov_b32_e32 v2, v0
	v_mov_b32_e32 v3, v0
	v_mov_b32_e32 v4, v0
	v_mov_b32_e32 v5, v0
	v_mov_b32_e32 v6, v0
	v_mov_b32_e32 v7, v0
	v_mov_b32_e32 v8, v0
	v_mov_b32_e32 v9, v0
	v_mov_b32_e32 v10, v0
	v_mov_b32_e32 v11, v0
	v_mov_b32_e32 v12, v0
	v_mov_b32_e32 v13, v0
	v_mov_b32_e32 v14, v0
	v_mov_b32_e32 v15, v0
	v_mov_b32_e32 v16, v0
	v_mov_b32_e32 v17, v0
	v_mov_b32_e32 v18, v0
	v_mov_b32_e32 v19, v0
	v_mov_b32_e32 v20, v0
	v_mov_b32_e32 v21, v0
	v_mov_b32_e32 v22, v0
	v_mov_b32_e32 v23, v0
	v_mov_b32_e32 v24, v0
	v_mov_b32_e32 v25, v0
	v_mov_b32_e32 v26, v0
	v_mov_b32_e32 v27, v0
	v_mov_b32_e32 v28, v0
	v_mov_b32_e32 v29, v0
	v_mov_b32_e32 v30, v0
	v_mov_b32_e32 v31, v0
	v_mov_b32_e32 v32, v0
	v_mov_b32_e32 v33, v0
	v_mov_b32_e32 v34, v0
	v_mov_b32_e32 v35, v0
	v_mov_b32_e32 v36, v0
	v_mov_b32_e32 v37, v0
	v_mov_b32_e32 v38, v0
	v_mov_b32_e32 v39, v0
	v_mov_b32_e32 v40, v0
	v_mov_b32_e32 v41, v0
	v_mov_b32_e32 v42, v0
	v_mov_b32_e32 v43, v0
	v_mov_b32_e32 v44, v0
	v_mov_b32_e32 v45, v0
	v_mov_b32_e32 v46, v0
	v_mov_b32_e32 v47, v0
	v_mov_b32_e32 v48, v0
	v_mov_b32_e32 v49, v0
	v_mov_b32_e32 v50, v0
	v_mov_b32_e32 v51, v0
	v_mov_b32_e32 v52, v0
	v_mov_b32_e32 v53, v0
	v_mov_b32_e32 v54, v0
	v_mov_b32_e32 v55, v0
	v_mov_b32_e32 v56, v0
	v_mov_b32_e32 v57, v0
	v_mov_b32_e32 v58, v0
	v_mov_b32_e32 v59, v0
	v_mov_b32_e32 v60, v0
	v_mov_b32_e32 v61, v0
	v_mov_b32_e32 v62, v0
	v_mov_b32_e32 v63, v0
	s_branch .LBB0_64

; template <int BN>
; DI void gemm_main(f32x16 (&acc)[2][BN / 64], const GDesc& cur, const GDesc& nxt, GRegs<BN>& R, bool preloaded, char* smem) {
;     ...
;   for (int k0 = 0; k0 < K; k0 += 128) {
;     __syncthreads();
;     GM_STORE(R.ra0, R.rb0)
;     __syncthreads();
;     if (k0 + 128 < K) GM_LOAD(R.ra0, R.rb0, ap, wp, lda, ldw, k0 + 128)
;     else if (nxt.valid) GM_LOAD(R.ra0, R.rb0, apn, wpn, nxt.lda, nxt.ldw, 0)
;     GM_COMPUTE()
;     __syncthreads();
;     GM_STORE(R.ra1, R.rb1)
;     __syncthreads();
;     if (k0 + 192 < K) GM_LOAD(R.ra1, R.rb1, ap, wp, lda, ldw, k0 + 192)
;     else if (nxt.valid) GM_LOAD(R.ra1, R.rb1, apn, wpn, nxt.lda, nxt.ldw, 64)
;     GM_COMPUTE()
.Lt1_g1:
	v_lshl_add_u64 v[130:131], v[130:131], 0, s[88:89]
	s_andn2_b64 vcc, exec, s[6:7]
	v_lshl_add_u64 v[132:133], v[132:133], 0, s[88:89]
	s_cbranch_vccz .LBB0_59
.LBB0_64:
	s_addk_i32 s10, 0x80
	s_cmpk_gt_u32 s10, 0x37f
	s_cselect_b64 s[6:7], -1, 0
	s_and_b64 vcc, exec, s[6:7]
	v_lshl_add_u64 v[136:137], v[132:133], 0, v[168:169]
	v_lshl_add_u64 v[134:135], v[130:131], 0, v[168:169]
	s_barrier
	s_waitcnt vmcnt(15)
	ds_write_b128 v128, v[64:67]
	s_waitcnt vmcnt(14)
	ds_write_b128 v128, v[72:75] offset:4608
	s_waitcnt vmcnt(13)
	ds_write_b128 v128, v[80:83] offset:9216
	s_waitcnt vmcnt(12)
	ds_write_b128 v128, v[88:91] offset:13824
	s_waitcnt vmcnt(11)
	ds_write_b128 v128, v[96:99] offset:18432
	s_waitcnt vmcnt(10)
	ds_write_b128 v128, v[104:107] offset:23040
	s_waitcnt vmcnt(9)
	ds_write_b128 v128, v[112:115] offset:27648
	s_waitcnt vmcnt(8)
	ds_write_b128 v128, v[120:123] offset:32256
	s_waitcnt lgkmcnt(0)
	s_barrier
	s_cbranch_vccnz .Lnopf_g1
	s_setprio 1
	ds_read_b128 v[140:143], v129
	ds_read_b128 v[144:147], v138 offset:23040
	ds_read_b128 v[148:151], v129 offset:4608
	ds_read_b128 v[152:155], v129 offset:32
	s_waitcnt lgkmcnt(2)
	v_mfma_f32_32x32x16_bf16 v[32:47], v[140:143], v[144:147], v[32:47]
	ds_read_b128 v[156:159], v138 offset:18432
	v_add_co_u32_e32 v64, vcc, 0x4110000, v136
	s_waitcnt lgkmcnt(0)
	v_mfma_f32_32x32x16_bf16 v[48:63], v[140:143], v[156:159], v[48:63]
	ds_read_b128 v[140:143], v138 offset:18464
	v_addc_co_u32_e32 v65, vcc, 0, v137, vcc
	v_add_co_u32_e32 v72, vcc, 0x4120000, v136
	v_mfma_f32_32x32x16_bf16 v[16:31], v[148:151], v[156:159], v[16:31]
	ds_read_b128 v[156:159], v129 offset:4640
	global_load_dwordx4 v[64:67], v[64:65], off offset:512
	v_addc_co_u32_e32 v73, vcc, 0, v137, vcc
	v_add_co_u32_e32 v80, vcc, 0x4130000, v136
	v_mfma_f32_32x32x16_bf16 v[0:15], v[148:151], v[144:147], v[0:15]
	ds_read_b128 v[144:147], v138 offset:23072
	global_load_dwordx4 v[72:75], v[72:73], off offset:512
	v_addc_co_u32_e32 v81, vcc, 0, v137, vcc
	v_add_co_u32_e32 v88, vcc, 0x4140000, v136
	s_waitcnt lgkmcnt(2)
	v_mfma_f32_32x32x16_bf16 v[48:63], v[152:155], v[140:143], v[48:63]
	ds_read_b128 v[148:151], v129 offset:64
	global_load_dwordx4 v[80:83], v[80:81], off offset:512
	v_addc_co_u32_e32 v89, vcc, 0, v137, vcc
	v_add_co_u32_e32 v96, vcc, 0x1600000, v134
	s_waitcnt lgkmcnt(1)
	v_mfma_f32_32x32x16_bf16 v[32:47], v[152:155], v[144:147], v[32:47]
	ds_read_b128 v[152:155], v129 offset:4672
	global_load_dwordx4 v[88:91], v[88:89], off offset:512
	v_addc_co_u32_e32 v97, vcc, 0, v135, vcc
	v_add_co_u32_e32 v104, vcc, 0x1610000, v134
	v_mfma_f32_32x32x16_bf16 v[16:31], v[156:159], v[140:143], v[16:31]
	ds_read_b128 v[140:143], v138 offset:18496
	global_load_dwordx4 v[96:99], v[96:97], off offset:256
	v_addc_co_u32_e32 v105, vcc, 0, v135, vcc
	v_add_co_u32_e32 v112, vcc, 0x1620000, v134
	v_mfma_f32_32x32x16_bf16 v[0:15], v[156:159], v[144:147], v[0:15]
	ds_read_b128 v[144:147], v138 offset:23104
	global_load_dwordx4 v[104:107], v[104:105], off offset:256
	v_addc_co_u32_e32 v113, vcc, 0, v135, vcc
	v_add_co_u32_e32 v120, vcc, 0x1630000, v134
	s_waitcnt lgkmcnt(1)
	v_mfma_f32_32x32x16_bf16 v[48:63], v[148:151], v[140:143], v[48:63]
	ds_read_b128 v[156:159], v129 offset:96
	global_load_dwordx4 v[112:115], v[112:113], off offset:256
	v_addc_co_u32_e32 v121, vcc, 0, v135, vcc
	s_waitcnt lgkmcnt(1)
	v_mfma_f32_32x32x16_bf16 v[32:47], v[148:151], v[144:147], v[32:47]
	ds_read_b128 v[148:151], v129 offset:4704
	global_load_dwordx4 v[120:123], v[120:121], off offset:256
	v_mfma_f32_32x32x16_bf16 v[16:31], v[152:155], v[140:143], v[16:31]
	ds_read_b128 v[140:143], v138 offset:18528
	v_mfma_f32_32x32x16_bf16 v[0:15], v[152:155], v[144:147], v[0:15]
	ds_read_b128 v[144:147], v138 offset:23136
	s_waitcnt lgkmcnt(1)
	v_mfma_f32_32x32x16_bf16 v[48:63], v[156:159], v[140:143], v[48:63]
	s_waitcnt lgkmcnt(0)
	v_mfma_f32_32x32x16_bf16 v[32:47], v[156:159], v[144:147], v[32:47]
	v_mfma_f32_32x32x16_bf16 v[16:31], v[148:151], v[140:143], v[16:31]
	v_mfma_f32_32x32x16_bf16 v[0:15], v[148:151], v[144:147], v[0:15]
	s_setprio 0
	s_branch .Lj0_g1

; template <int BN>
; DI void gemm_main(f32x16 (&acc)[2][BN / 64], const GDesc& cur, const GDesc& nxt, GRegs<BN>& R, bool preloaded, char* smem) {
;     ...
;   for (int k0 = 0; k0 < K; k0 += 128) {
;     __syncthreads();
;     GM_STORE(R.ra0, R.rb0)
;     __syncthreads();
;     if (k0 + 128 < K) GM_LOAD(R.ra0, R.rb0, ap, wp, lda, ldw, k0 + 128)
;     else if (nxt.valid) GM_LOAD(R.ra0, R.rb0, apn, wpn, nxt.lda, nxt.ldw, 0)
;     GM_COMPUTE()
;     __syncthreads();
;     GM_STORE(R.ra1, R.rb1)
;     __syncthreads();
;     if (k0 + 192 < K) GM_LOAD(R.ra1, R.rb1, ap, wp, lda, ldw, k0 + 192)
;     else if (nxt.valid) GM_LOAD(R.ra1, R.rb1, apn, wpn, nxt.lda, nxt.ldw, 64)
;     GM_COMPUTE()
.Lj0_g1:
	s_cmpk_gt_u32 s10, 0x33f
	s_barrier
	s_waitcnt vmcnt(15)
	ds_write_b128 v128, v[68:71]
	s_waitcnt vmcnt(14)
	ds_write_b128 v128, v[76:79] offset:4608
	s_waitcnt vmcnt(13)
	ds_write_b128 v128, v[84:87] offset:9216
	s_waitcnt vmcnt(12)
	ds_write_b128 v128, v[92:95] offset:13824
	s_waitcnt vmcnt(11)
	ds_write_b128 v128, v[100:103] offset:18432
	s_waitcnt vmcnt(10)
	ds_write_b128 v128, v[108:111] offset:23040
	s_waitcnt vmcnt(9)
	ds_write_b128 v128, v[116:119] offset:27648
	s_waitcnt vmcnt(8)
	ds_write_b128 v128, v[124:127] offset:32256
	s_waitcnt lgkmcnt(0)
	s_barrier
	s_cbranch_scc1 .LBB0_63
	s_setprio 1
	ds_read_b128 v[160:163], v129
	ds_read_b128 v[140:143], v138 offset:23040
	ds_read_b128 v[144:147], v129 offset:4608
	ds_read_b128 v[148:151], v129 offset:32
	s_waitcnt lgkmcnt(2)
	v_mfma_f32_32x32x16_bf16 v[32:47], v[160:163], v[140:143], v[32:47]
	ds_read_b128 v[152:155], v138 offset:18432
	v_add_co_u32_e32 v68, vcc, 0x4110000, v136
	s_waitcnt lgkmcnt(0)
	v_mfma_f32_32x32x16_bf16 v[48:63], v[160:163], v[152:155], v[48:63]
	ds_read_b128 v[160:163], v138 offset:18464
	v_addc_co_u32_e32 v69, vcc, 0, v137, vcc
	v_add_co_u32_e32 v76, vcc, 0x4120000, v136
	v_mfma_f32_32x32x16_bf16 v[16:31], v[144:147], v[152:155], v[16:31]
	ds_read_b128 v[152:155], v129 offset:4640
	global_load_dwordx4 v[68:71], v[68:69], off offset:640
	v_addc_co_u32_e32 v77, vcc, 0, v137, vcc
	v_add_co_u32_e32 v84, vcc, 0x4130000, v136
	v_mfma_f32_32x32x16_bf16 v[0:15], v[144:147], v[140:143], v[0:15]
	ds_read_b128 v[140:143], v138 offset:23072
	global_load_dwordx4 v[76:79], v[76:77], off offset:640
	v_addc_co_u32_e32 v85, vcc, 0, v137, vcc
	v_add_co_u32_e32 v92, vcc, 0x4140000, v136
	s_waitcnt lgkmcnt(2)
	v_mfma_f32_32x32x16_bf16 v[48:63], v[148:151], v[160:163], v[48:63]
	ds_read_b128 v[144:147], v129 offset:64
	global_load_dwordx4 v[84:87], v[84:85], off offset:640
	v_addc_co_u32_e32 v93, vcc, 0, v137, vcc
	v_add_co_u32_e32 v100, vcc, 0x1600000, v134
	s_waitcnt lgkmcnt(1)
	v_mfma_f32_32x32x16_bf16 v[32:47], v[148:151], v[140:143], v[32:47]
	ds_read_b128 v[148:151], v129 offset:4672
	global_load_dwordx4 v[92:95], v[92:93], off offset:640
	v_addc_co_u32_e32 v101, vcc, 0, v135, vcc
	v_add_co_u32_e32 v108, vcc, 0x1610000, v134
	v_mfma_f32_32x32x16_bf16 v[16:31], v[152:155], v[160:163], v[16:31]
	ds_read_b128 v[160:163], v138 offset:18496
	global_load_dwordx4 v[100:103], v[100:101], off offset:384
	v_addc_co_u32_e32 v109, vcc, 0, v135, vcc
	v_add_co_u32_e32 v116, vcc, 0x1620000, v134
	v_mfma_f32_32x32x16_bf16 v[0:15], v[152:155], v[140:143], v[0:15]
	ds_read_b128 v[140:143], v138 offset:23104
	global_load_dwordx4 v[108:111], v[108:109], off offset:384
	v_addc_co_u32_e32 v117, vcc, 0, v135, vcc
	v_add_co_u32_e32 v124, vcc, 0x1630000, v134
	s_waitcnt lgkmcnt(1)
	v_mfma_f32_32x32x16_bf16 v[48:63], v[144:147], v[160:163], v[48:63]
	ds_read_b128 v[152:155], v129 offset:96
	global_load_dwordx4 v[116:119], v[116:117], off offset:384
	v_addc_co_u32_e32 v125, vcc, 0, v135, vcc
	s_waitcnt lgkmcnt(1)
	v_mfma_f32_32x32x16_bf16 v[32:47], v[144:147], v[140:143], v[32:47]
	ds_read_b128 v[144:147], v129 offset:4704
	global_load_dwordx4 v[124:127], v[124:125], off offset:384
	v_mfma_f32_32x32x16_bf16 v[16:31], v[148:151], v[160:163], v[16:31]
	ds_read_b128 v[160:163], v138 offset:18528
	v_mfma_f32_32x32x16_bf16 v[0:15], v[148:151], v[140:143], v[0:15]
	ds_read_b128 v[140:143], v138 offset:23136
	s_waitcnt lgkmcnt(1)
	v_mfma_f32_32x32x16_bf16 v[48:63], v[152:155], v[160:163], v[48:63]
	s_waitcnt lgkmcnt(0)
	v_mfma_f32_32x32x16_bf16 v[32:47], v[152:155], v[140:143], v[32:47]
	v_mfma_f32_32x32x16_bf16 v[16:31], v[144:147], v[160:163], v[16:31]
	v_mfma_f32_32x32x16_bf16 v[0:15], v[144:147], v[140:143], v[0:15]
	s_setprio 0
	s_branch .Lt1_g1
.Lnopf_g1:
	s_waitcnt vmcnt(0)
	s_branch .LBB0_66

; template <int BN>
; DI void gemm_main(f32x16 (&acc)[2][BN / 64], const GDesc& cur, const GDesc& nxt, GRegs<BN>& R, bool preloaded, char* smem) {
;     ...
;   const u16* ap = cur.A + (size_t)(cur.m0 + (tid >> 3)) * cur.lda + (tid & 7) * 8;
;   const u16* wp = cur.W + (size_t)(cur.n0 + (tid >> 3)) * cur.ldw + (tid & 7) * 8;
;   const u16* apn = nxt.A + (size_t)(nxt.m0 + (tid >> 3)) * nxt.lda + (tid & 7) * 8;
;   const u16* wpn = nxt.W + (size_t)(nxt.n0 + (tid >> 3)) * nxt.ldw + (tid & 7) * 8;
;   const int lda = cur.lda, ldw = cur.ldw, K = cur.K;
;   u16* asw = As + (tid >> 3) * 72 + (tid & 7) * 8;
;   u16* bsw = Bs + (tid >> 3) * 72 + (tid & 7) * 8;
;     ...
;   if (!preloaded) {
;     GM_LOAD(R.ra0, R.rb0, ap, wp, lda, ldw, 0)
;     GM_LOAD(R.ra1, R.rb1, ap, wp, lda, ldw, 64)
;   }
.LBB0_121:
	s_lshl_b32 s6, s6, 6
	s_sub_i32 s6, s4, s6
	s_ashr_i32 s12, s6, 3
	v_mov_b32_e32 v18, v171
	s_bfe_u32 s7, s4, 0x30003
	s_and_b32 s6, s12, 0x1fffff8
	s_lshl_b32 s8, s9, 7
	s_or_b32 s6, s6, s7
	v_ashrrev_i32_e32 v19, 3, v18
	v_add_u32_e32 v0, s8, v19
	s_lshl_b32 s11, s7, 7
	s_lshl_b32 s10, s6, 7
	v_ashrrev_i32_e32 v1, 31, v0
	v_readlane_b32 s6, v251, 10
	v_lshlrev_b64 v[0:1], 11, v[0:1]
	v_readlane_b32 s7, v251, 11
	v_lshlrev_b32_e32 v4, 4, v18
	s_waitcnt vmcnt(0)
	v_and_b32_e32 v168, 0x70, v4
	v_lshl_add_u64 v[2:3], s[6:7], 0, v[0:1]
	v_lshl_add_u64 v[2:3], v[2:3], 0, v[168:169]
	s_mov_b32 s13, 0x10000
	v_add_co_u32_e32 v6, vcc, s13, v2
	v_add_u32_e32 v4, s10, v19
	s_nop 0
	v_addc_co_u32_e32 v7, vcc, 0, v3, vcc
	s_mov_b32 s14, 0x20000
	v_ashrrev_i32_e32 v5, 31, v4
	v_readlane_b32 s6, v254, 26
	v_add_co_u32_e32 v8, vcc, s14, v2
	v_lshlrev_b64 v[4:5], 11, v[4:5]
	v_readlane_b32 s7, v254, 27
	v_addc_co_u32_e32 v9, vcc, 0, v3, vcc
	s_mov_b32 s15, 0x30000
	v_lshl_add_u64 v[4:5], s[6:7], 0, v[4:5]
	v_add_co_u32_e32 v10, vcc, s15, v2
	v_lshl_add_u64 v[4:5], v[4:5], 0, v[168:169]
	s_nop 0
	v_addc_co_u32_e32 v11, vcc, 0, v3, vcc
	v_add_co_u32_e32 v12, vcc, s13, v4
	v_mad_u64_u32 v[128:129], s[6:7], v19, s53, v[168:169]
	s_nop 0
	v_addc_co_u32_e32 v13, vcc, 0, v5, vcc
	v_add_co_u32_e32 v14, vcc, s14, v4
	s_lshl_b32 s6, s12, 7
	s_nop 0
	v_addc_co_u32_e32 v15, vcc, 0, v5, vcc
	v_add_co_u32_e32 v16, vcc, s15, v4
	s_and_b32 s6, s6, 0xfffffc00
	s_nop 0
	v_addc_co_u32_e32 v17, vcc, 0, v5, vcc
	global_load_dwordx4 v[64:67], v[2:3], off
	global_load_dwordx4 v[72:75], v[6:7], off
	global_load_dwordx4 v[80:83], v[8:9], off
	global_load_dwordx4 v[88:91], v[10:11], off
	global_load_dwordx4 v[96:99], v[4:5], off
	global_load_dwordx4 v[104:107], v[12:13], off
	global_load_dwordx4 v[112:115], v[14:15], off
	global_load_dwordx4 v[120:123], v[16:17], off
	global_load_dwordx4 v[68:71], v[2:3], off offset:128
	global_load_dwordx4 v[76:79], v[6:7], off offset:128
	global_load_dwordx4 v[84:87], v[8:9], off offset:128
	global_load_dwordx4 v[92:95], v[10:11], off offset:128
	global_load_dwordx4 v[100:103], v[4:5], off offset:128
	global_load_dwordx4 v[108:111], v[12:13], off offset:128
	global_load_dwordx4 v[116:119], v[14:15], off offset:128
	global_load_dwordx4 v[124:127], v[16:17], off offset:128
	v_and_b32_e32 v2, 31, v18
	v_lshrrev_b32_e32 v3, 1, v18
	v_and_or_b32 v2, v3, s54, v2
	v_mul_lo_u32 v5, v2, s53
	v_and_b32_e32 v2, 7, v18
	s_or_b32 s6, s11, s6
	v_and_b32_e32 v4, 16, v3
	v_and_b32_e32 v3, 0x5f, v18
	v_lshlrev_b32_e32 v168, 4, v2
	v_add_u32_e32 v2, s6, v19
	v_mul_u32_u24_e32 v6, 0x90, v3
	v_ashrrev_i32_e32 v3, 31, v2
	v_readlane_b32 s6, v254, 31
	v_lshlrev_b64 v[2:3], 11, v[2:3]
	v_readlane_b32 s7, v254, 32
	v_lshl_add_u64 v[132:133], s[76:77], 0, v[0:1]
	v_mov_b32_e32 v0, 0
	v_readlane_b32 s12, v251, 12
	s_mov_b32 s22, 0x78787879
	s_movk_i32 s23, 0xef00
	s_movk_i32 s24, 0x100
	v_readlane_b32 s28, v254, 7
	v_lshl_add_u64 v[130:131], s[6:7], 0, v[2:3]
	s_movk_i32 s11, 0xff80
	v_add_u32_e32 v129, v4, v5
	v_add_u32_e32 v138, v4, v6
	v_mov_b32_e32 v1, v0
	v_mov_b32_e32 v2, v0
	v_mov_b32_e32 v3, v0
	v_mov_b32_e32 v4, v0
	v_mov_b32_e32 v5, v0
	v_mov_b32_e32 v6, v0
	v_mov_b32_e32 v7, v0
	v_mov_b32_e32 v8, v0
	v_mov_b32_e32 v9, v0
	v_mov_b32_e32 v10, v0
	v_mov_b32_e32 v11, v0
	v_mov_b32_e32 v12, v0
	v_mov_b32_e32 v13, v0
	v_mov_b32_e32 v14, v0
	v_mov_b32_e32 v15, v0
	v_mov_b32_e32 v32, v0
	v_mov_b32_e32 v33, v0
	v_mov_b32_e32 v34, v0
	v_mov_b32_e32 v35, v0
	v_mov_b32_e32 v36, v0
	v_mov_b32_e32 v37, v0
	v_mov_b32_e32 v38, v0
	v_mov_b32_e32 v39, v0
	v_mov_b32_e32 v40, v0
	v_mov_b32_e32 v41, v0
	v_mov_b32_e32 v42, v0
	v_mov_b32_e32 v43, v0
	v_mov_b32_e32 v44, v0
	v_mov_b32_e32 v45, v0
	v_mov_b32_e32 v46, v0
	v_mov_b32_e32 v47, v0
	v_mov_b32_e32 v16, v0
	v_mov_b32_e32 v17, v0
	v_mov_b32_e32 v18, v0
	v_mov_b32_e32 v19, v0
	v_mov_b32_e32 v20, v0
	v_mov_b32_e32 v21, v0
	v_mov_b32_e32 v22, v0
	v_mov_b32_e32 v23, v0
	v_mov_b32_e32 v24, v0
	v_mov_b32_e32 v25, v0
	v_mov_b32_e32 v26, v0
	v_mov_b32_e32 v27, v0
	v_mov_b32_e32 v28, v0
	v_mov_b32_e32 v29, v0
	v_mov_b32_e32 v30, v0
	v_mov_b32_e32 v31, v0
	v_mov_b32_e32 v48, v0
	v_mov_b32_e32 v49, v0
	v_mov_b32_e32 v50, v0
	v_mov_b32_e32 v51, v0
	v_mov_b32_e32 v52, v0
	v_mov_b32_e32 v53, v0
	v_mov_b32_e32 v54, v0
	v_mov_b32_e32 v55, v0
	v_mov_b32_e32 v56, v0
	v_mov_b32_e32 v57, v0
	v_mov_b32_e32 v58, v0
	v_mov_b32_e32 v59, v0
	v_mov_b32_e32 v60, v0
	v_mov_b32_e32 v61, v0
	v_mov_b32_e32 v62, v0
	v_mov_b32_e32 v63, v0
	v_readlane_b32 s13, v251, 13
	v_readlane_b32 s44, v252, 33
	v_readlane_b32 s29, v254, 8
	v_readlane_b32 s30, v254, 9
	v_readlane_b32 s31, v254, 10
	v_readlane_b32 s45, v252, 34
	v_readlane_b32 s46, v252, 35
	v_readlane_b32 s47, v252, 36
	v_readlane_b32 s48, v252, 37
	v_readlane_b32 s49, v252, 38
	v_readlane_b32 s50, v252, 39
	v_readlane_b32 s51, v252, 40
	v_readlane_b32 s52, v252, 41
	v_readlane_b32 s53, v252, 42
	v_readlane_b32 s54, v252, 43
	v_readlane_b32 s55, v252, 44
	v_readlane_b32 s56, v252, 45
	v_readlane_b32 s57, v252, 46
	v_readlane_b32 s58, v252, 47
	v_readlane_b32 s59, v252, 48
	s_branch .LBB0_123

; template <int BN>
; DI void gemm_main(f32x16 (&acc)[2][BN / 64], const GDesc& cur, const GDesc& nxt, GRegs<BN>& R, bool preloaded, char* smem) {
;     ...
;   for (int k0 = 0; k0 < K; k0 += 128) {
;     __syncthreads();
;     GM_STORE(R.ra0, R.rb0)
;     __syncthreads();
;     if (k0 + 128 < K) GM_LOAD(R.ra0, R.rb0, ap, wp, lda, ldw, k0 + 128)
;     else if (nxt.valid) GM_LOAD(R.ra0, R.rb0, apn, wpn, nxt.lda, nxt.ldw, 0)
;     GM_COMPUTE()
;     __syncthreads();
;     GM_STORE(R.ra1, R.rb1)
;     __syncthreads();
;     if (k0 + 192 < K) GM_LOAD(R.ra1, R.rb1, ap, wp, lda, ldw, k0 + 192)
;     else if (nxt.valid) GM_LOAD(R.ra1, R.rb1, apn, wpn, nxt.lda, nxt.ldw, 64)
;     GM_COMPUTE()
.LBB0_123:
	s_addk_i32 s11, 0x80
	s_cmpk_gt_u32 s11, 0x37f
	s_cselect_b64 s[6:7], -1, 0
	s_and_b64 vcc, exec, s[6:7]
	v_lshl_add_u64 v[136:137], v[132:133], 0, v[168:169]
	v_lshl_add_u64 v[134:135], v[130:131], 0, v[168:169]
	s_waitcnt vmcnt(63) expcnt(7) lgkmcnt(15)
	s_barrier
	s_waitcnt vmcnt(15)
	ds_write_b128 v128, v[64:67]
	s_waitcnt vmcnt(14)
	ds_write_b128 v128, v[72:75] offset:4608
	s_waitcnt vmcnt(13)
	ds_write_b128 v128, v[80:83] offset:9216
	s_waitcnt vmcnt(12)
	ds_write_b128 v128, v[88:91] offset:13824
	s_waitcnt vmcnt(11)
	ds_write_b128 v128, v[96:99] offset:18432
	s_waitcnt vmcnt(10)
	ds_write_b128 v128, v[104:107] offset:23040
	s_waitcnt vmcnt(9)
	ds_write_b128 v128, v[112:115] offset:27648
	s_waitcnt vmcnt(8)
	ds_write_b128 v128, v[120:123] offset:32256
	s_waitcnt lgkmcnt(0)
	s_barrier
	s_cbranch_vccnz .Lnopf_g2
	s_setprio 1
	ds_read_b128 v[140:143], v129
	ds_read_b128 v[144:147], v138 offset:23040
	ds_read_b128 v[148:151], v129 offset:4608
	ds_read_b128 v[152:155], v129 offset:32
	s_waitcnt lgkmcnt(2)
	v_mfma_f32_32x32x16_bf16 v[16:31], v[140:143], v[144:147], v[16:31]
	ds_read_b128 v[156:159], v138 offset:18432
	v_add_co_u32_e32 v64, vcc, 0x10d10000, v136
	s_waitcnt lgkmcnt(0)
	v_mfma_f32_32x32x16_bf16 v[48:63], v[140:143], v[156:159], v[48:63]
	ds_read_b128 v[140:143], v138 offset:18464
	v_addc_co_u32_e32 v65, vcc, 0, v137, vcc
	v_add_co_u32_e32 v72, vcc, 0x10d20000, v136
	v_mfma_f32_32x32x16_bf16 v[32:47], v[148:151], v[156:159], v[32:47]
	ds_read_b128 v[156:159], v129 offset:4640
	global_load_dwordx4 v[64:67], v[64:65], off offset:512
	v_addc_co_u32_e32 v73, vcc, 0, v137, vcc
	v_add_co_u32_e32 v80, vcc, 0x10d30000, v136
	v_mfma_f32_32x32x16_bf16 v[0:15], v[148:151], v[144:147], v[0:15]
	ds_read_b128 v[144:147], v138 offset:23072
	global_load_dwordx4 v[72:75], v[72:73], off offset:512
	v_addc_co_u32_e32 v81, vcc, 0, v137, vcc
	v_add_co_u32_e32 v88, vcc, 0x10d40000, v136
	s_waitcnt lgkmcnt(2)
	v_mfma_f32_32x32x16_bf16 v[48:63], v[152:155], v[140:143], v[48:63]
	ds_read_b128 v[148:151], v129 offset:64
	global_load_dwordx4 v[80:83], v[80:81], off offset:512
	v_addc_co_u32_e32 v89, vcc, 0, v137, vcc
	v_add_co_u32_e32 v96, vcc, 0x1400000, v134
	s_waitcnt lgkmcnt(1)
	v_mfma_f32_32x32x16_bf16 v[16:31], v[152:155], v[144:147], v[16:31]
	ds_read_b128 v[152:155], v129 offset:4672
	global_load_dwordx4 v[88:91], v[88:89], off offset:512
	v_addc_co_u32_e32 v97, vcc, 0, v135, vcc
	v_add_co_u32_e32 v104, vcc, 0x1410000, v134
	v_mfma_f32_32x32x16_bf16 v[32:47], v[156:159], v[140:143], v[32:47]
	ds_read_b128 v[140:143], v138 offset:18496
	global_load_dwordx4 v[96:99], v[96:97], off offset:256
	v_addc_co_u32_e32 v105, vcc, 0, v135, vcc
	v_add_co_u32_e32 v112, vcc, 0x1420000, v134
	v_mfma_f32_32x32x16_bf16 v[0:15], v[156:159], v[144:147], v[0:15]
	ds_read_b128 v[144:147], v138 offset:23104
	global_load_dwordx4 v[104:107], v[104:105], off offset:256
	v_addc_co_u32_e32 v113, vcc, 0, v135, vcc
	v_add_co_u32_e32 v120, vcc, 0x1430000, v134
	s_waitcnt lgkmcnt(1)
	v_mfma_f32_32x32x16_bf16 v[48:63], v[148:151], v[140:143], v[48:63]
	ds_read_b128 v[156:159], v129 offset:96
	global_load_dwordx4 v[112:115], v[112:113], off offset:256
	v_addc_co_u32_e32 v121, vcc, 0, v135, vcc
	s_waitcnt lgkmcnt(1)
	v_mfma_f32_32x32x16_bf16 v[16:31], v[148:151], v[144:147], v[16:31]
	ds_read_b128 v[148:151], v129 offset:4704
	global_load_dwordx4 v[120:123], v[120:121], off offset:256
	v_mfma_f32_32x32x16_bf16 v[32:47], v[152:155], v[140:143], v[32:47]
	ds_read_b128 v[140:143], v138 offset:18528
	v_mfma_f32_32x32x16_bf16 v[0:15], v[152:155], v[144:147], v[0:15]
	ds_read_b128 v[144:147], v138 offset:23136
	s_waitcnt lgkmcnt(1)
	v_mfma_f32_32x32x16_bf16 v[48:63], v[156:159], v[140:143], v[48:63]
	s_waitcnt lgkmcnt(0)
	v_mfma_f32_32x32x16_bf16 v[16:31], v[156:159], v[144:147], v[16:31]
	v_mfma_f32_32x32x16_bf16 v[32:47], v[148:151], v[140:143], v[32:47]
	v_mfma_f32_32x32x16_bf16 v[0:15], v[148:151], v[144:147], v[0:15]
	s_setprio 0
	s_branch .Lj0_g2

; template <int BN>
; DI void gemm_main(f32x16 (&acc)[2][BN / 64], const GDesc& cur, const GDesc& nxt, GRegs<BN>& R, bool preloaded, char* smem) {
;     ...
;   for (int k0 = 0; k0 < K; k0 += 128) {
;     __syncthreads();
;     GM_STORE(R.ra0, R.rb0)
;     __syncthreads();
;     if (k0 + 128 < K) GM_LOAD(R.ra0, R.rb0, ap, wp, lda, ldw, k0 + 128)
;     else if (nxt.valid) GM_LOAD(R.ra0, R.rb0, apn, wpn, nxt.lda, nxt.ldw, 0)
;     GM_COMPUTE()
;     __syncthreads();
;     GM_STORE(R.ra1, R.rb1)
;     __syncthreads();
;     if (k0 + 192 < K) GM_LOAD(R.ra1, R.rb1, ap, wp, lda, ldw, k0 + 192)
;     else if (nxt.valid) GM_LOAD(R.ra1, R.rb1, apn, wpn, nxt.lda, nxt.ldw, 64)
;     GM_COMPUTE()
.Lj0_g2:
	s_cmpk_gt_u32 s11, 0x33f
	s_barrier
	s_waitcnt vmcnt(15)
	ds_write_b128 v128, v[68:71]
	s_waitcnt vmcnt(14)
	ds_write_b128 v128, v[76:79] offset:4608
	s_waitcnt vmcnt(13)
	ds_write_b128 v128, v[84:87] offset:9216
	s_waitcnt vmcnt(12)
	ds_write_b128 v128, v[92:95] offset:13824
	s_waitcnt vmcnt(11)
	ds_write_b128 v128, v[100:103] offset:18432
	s_waitcnt vmcnt(10)
	ds_write_b128 v128, v[108:111] offset:23040
	s_waitcnt vmcnt(9)
	ds_write_b128 v128, v[116:119] offset:27648
	s_waitcnt vmcnt(8)
	ds_write_b128 v128, v[124:127] offset:32256
	s_waitcnt lgkmcnt(0)
	s_barrier
	s_cbranch_scc1 .LBB0_122
	s_setprio 1
	ds_read_b128 v[160:163], v129
	ds_read_b128 v[140:143], v138 offset:23040
	ds_read_b128 v[144:147], v129 offset:4608
	ds_read_b128 v[148:151], v129 offset:32
	s_waitcnt lgkmcnt(2)
	v_mfma_f32_32x32x16_bf16 v[16:31], v[160:163], v[140:143], v[16:31]
	ds_read_b128 v[152:155], v138 offset:18432
	v_add_co_u32_e32 v68, vcc, 0x10d10000, v136
	s_waitcnt lgkmcnt(0)
	v_mfma_f32_32x32x16_bf16 v[48:63], v[160:163], v[152:155], v[48:63]
	ds_read_b128 v[160:163], v138 offset:18464
	v_addc_co_u32_e32 v69, vcc, 0, v137, vcc
	v_add_co_u32_e32 v76, vcc, 0x10d20000, v136
	v_mfma_f32_32x32x16_bf16 v[32:47], v[144:147], v[152:155], v[32:47]
	ds_read_b128 v[152:155], v129 offset:4640
	global_load_dwordx4 v[68:71], v[68:69], off offset:640
	v_addc_co_u32_e32 v77, vcc, 0, v137, vcc
	v_add_co_u32_e32 v84, vcc, 0x10d30000, v136
	v_mfma_f32_32x32x16_bf16 v[0:15], v[144:147], v[140:143], v[0:15]
	ds_read_b128 v[140:143], v138 offset:23072
	global_load_dwordx4 v[76:79], v[76:77], off offset:640
	v_addc_co_u32_e32 v85, vcc, 0, v137, vcc
	v_add_co_u32_e32 v92, vcc, 0x10d40000, v136
	s_waitcnt lgkmcnt(2)
	v_mfma_f32_32x32x16_bf16 v[48:63], v[148:151], v[160:163], v[48:63]
	ds_read_b128 v[144:147], v129 offset:64
	global_load_dwordx4 v[84:87], v[84:85], off offset:640
	v_addc_co_u32_e32 v93, vcc, 0, v137, vcc
	v_add_co_u32_e32 v100, vcc, 0x1400000, v134
	s_waitcnt lgkmcnt(1)
	v_mfma_f32_32x32x16_bf16 v[16:31], v[148:151], v[140:143], v[16:31]
	ds_read_b128 v[148:151], v129 offset:4672
	global_load_dwordx4 v[92:95], v[92:93], off offset:640
	v_addc_co_u32_e32 v101, vcc, 0, v135, vcc
	v_add_co_u32_e32 v108, vcc, 0x1410000, v134
	v_mfma_f32_32x32x16_bf16 v[32:47], v[152:155], v[160:163], v[32:47]
	ds_read_b128 v[160:163], v138 offset:18496
	global_load_dwordx4 v[100:103], v[100:101], off offset:384
	v_addc_co_u32_e32 v109, vcc, 0, v135, vcc
	v_add_co_u32_e32 v116, vcc, 0x1420000, v134
	v_mfma_f32_32x32x16_bf16 v[0:15], v[152:155], v[140:143], v[0:15]
	ds_read_b128 v[140:143], v138 offset:23104
	global_load_dwordx4 v[108:111], v[108:109], off offset:384
	v_addc_co_u32_e32 v117, vcc, 0, v135, vcc
	v_add_co_u32_e32 v124, vcc, 0x1430000, v134
	s_waitcnt lgkmcnt(1)
	v_mfma_f32_32x32x16_bf16 v[48:63], v[144:147], v[160:163], v[48:63]
	ds_read_b128 v[152:155], v129 offset:96
	global_load_dwordx4 v[116:119], v[116:117], off offset:384
	v_addc_co_u32_e32 v125, vcc, 0, v135, vcc
	s_waitcnt lgkmcnt(1)
	v_mfma_f32_32x32x16_bf16 v[16:31], v[144:147], v[140:143], v[16:31]
	ds_read_b128 v[144:147], v129 offset:4704
	global_load_dwordx4 v[124:127], v[124:125], off offset:384
	v_mfma_f32_32x32x16_bf16 v[32:47], v[148:151], v[160:163], v[32:47]
	ds_read_b128 v[160:163], v138 offset:18528
	v_mfma_f32_32x32x16_bf16 v[0:15], v[148:151], v[140:143], v[0:15]
	ds_read_b128 v[140:143], v138 offset:23136
	s_waitcnt lgkmcnt(1)
	v_mfma_f32_32x32x16_bf16 v[48:63], v[152:155], v[160:163], v[48:63]
	s_waitcnt lgkmcnt(0)
	v_mfma_f32_32x32x16_bf16 v[16:31], v[152:155], v[140:143], v[16:31]
	v_mfma_f32_32x32x16_bf16 v[32:47], v[144:147], v[160:163], v[32:47]
	v_mfma_f32_32x32x16_bf16 v[0:15], v[144:147], v[140:143], v[0:15]
	s_setprio 0
	s_branch .Lt1_g2

; #define MFMA32(a, b, c) __builtin_amdgcn_mfma_f32_32x32x16_bf16((a), (b), (c), 0, 0, 0)
; template <int DK, int DV>
; DI void attn_map(f32x16 (&O)[DV / 32], float& lsum, const u16* qrow, const u16* K1, int ldk1, const u16* K2, int ldk2, const u16* Vt, int nkeys, char* smem) {
;     ...
;   for (int k0 = 0; k0 < nkeys; k0 += 64) {
;     __syncthreads();
; #pragma unroll
;     for (int i = 0; i < NKR; ++i) { int id = tid + i * 256; int row = id / KCH, cc = id - row * KCH; *(u32x4*)(Ks + row * KST + cc * 8) = kreg[i]; }
; #pragma unroll
;     for (int i = 0; i < NVR; ++i) {
;       int id = tid + i * 256; int row = id >> 3, cc = id & 7;
;       u16* base = Vs + row * VST + (cc >> 1) * 16 + (cc & 1) * 4;
;       u32x2 t0 = {vreg[i].x, vreg[i].y}, t1 = {vreg[i].z, vreg[i].w};
;       *(u32x2*)base = t0; *(u32x2*)(base + 8) = t1;
;     }
;     __syncthreads();
;     if (k0 + 64 < nkeys) ATT_LOAD(k0 + 64)
;     f32x16 s[2];
;     __builtin_amdgcn_s_setprio(1);
; #pragma unroll
;     for (int j = 0; j < 2; ++j) {
; #pragma unroll
;       for (int ks = 0; ks < DK / 16; ++ks) {
;         bf16x8 kf = *(const bf16x8*)(Ks + (j * 32 + r) * KST + ks * 16 + 8 * h);
;         s[j] = (ks == 0) ? MFMA32(kf, qf[ks], negm) : MFMA32(kf, qf[ks], s[j]);
;       }
;     }
;     {
;       constexpr int NQK = 2 * (DK / 16);
;       __builtin_amdgcn_sched_group_barrier(0x100, 2, 0);
; #pragma unroll
;       for (int q = 0; q < NQK - 2; ++q) { __builtin_amdgcn_sched_group_barrier(0x008, 1, 0); __builtin_amdgcn_sched_group_barrier(0x100, 1, 0); }
;       __builtin_amdgcn_sched_group_barrier(0x008, 2, 0);
;     }
;     __builtin_amdgcn_s_setprio(0);
.LBB0_382:
	s_cmpk_gt_u32 s10, 0x10bf
	s_cselect_b64 s[8:9], -1, 0
	s_and_b64 vcc, exec, s[8:9]
	s_barrier
	s_waitcnt vmcnt(5)
	ds_write_b128 v188, v[144:147]
	s_waitcnt vmcnt(4)
	ds_write_b128 v189, v[148:151]
	s_waitcnt vmcnt(3)
	ds_write2_b64 v190, v[152:153], v[154:155] offset0:128 offset1:130
	s_waitcnt vmcnt(2)
	ds_write2_b64 v191, v[156:157], v[158:159] offset0:128 offset1:130
	s_waitcnt vmcnt(1)
	ds_write2_b64 v192, v[160:161], v[162:163] offset0:128 offset1:130
	s_waitcnt vmcnt(0)
	ds_write2_b64 v193, v[164:165], v[166:167] offset0:128 offset1:130
	s_waitcnt lgkmcnt(0)
	s_barrier
	s_cbranch_vccnz .Lqk_last_A
	s_setprio 1
	ds_read_b128 v[200:203], v168
	ds_read_b128 v[204:207], v168 offset:32
	ds_read_b128 v[208:211], v168 offset:64
	ds_read_b128 v[212:215], v168 offset:96
	ds_read_b128 v[216:219], v168 offset:4608
	ds_read_b128 v[220:223], v168 offset:4640
	ds_read_b128 v[224:227], v168 offset:4672
	ds_read_b128 v[228:231], v168 offset:4704
	s_waitcnt lgkmcnt(7)
	v_mfma_f32_32x32x16_bf16 v[96:111], v[200:203], v[128:131], v[16:31]
	ds_read_b128 v[200:203], v168 offset:9216
	v_lshl_add_u64 v[236:237], v[186:187], 0, s[6:7]
	global_load_dwordx4 v[144:147], v[236:237], off
	s_waitcnt lgkmcnt(7)
	v_mfma_f32_32x32x16_bf16 v[96:111], v[204:207], v[132:135], v[96:111]
	ds_read_b128 v[204:207], v168 offset:13824
	v_lshl_add_u64 v[236:237], v[184:185], 0, s[6:7]
	global_load_dwordx4 v[148:151], v[236:237], off
	s_waitcnt lgkmcnt(7)
	v_mfma_f32_32x32x16_bf16 v[96:111], v[208:211], v[136:139], v[96:111]
	ds_read_b128 v[208:211], v168 offset:18432
	v_lshl_add_u64 v[236:237], v[182:183], 0, s[6:7]
	global_load_dwordx4 v[152:155], v[236:237], off
	s_waitcnt lgkmcnt(7)
	v_mfma_f32_32x32x16_bf16 v[96:111], v[212:215], v[140:143], v[96:111]
	ds_read_b128 v[212:215], v168 offset:23040
	v_lshl_add_u64 v[236:237], v[180:181], 0, s[6:7]
	global_load_dwordx4 v[156:159], v[236:237], off
	s_waitcnt lgkmcnt(7)
	v_mfma_f32_32x32x16_bf16 v[112:127], v[216:219], v[128:131], v[16:31]
	ds_read_b128 v[216:219], v168 offset:9248
	v_lshl_add_u64 v[236:237], v[178:179], 0, s[6:7]
	global_load_dwordx4 v[160:163], v[236:237], off
	s_waitcnt lgkmcnt(7)
	v_mfma_f32_32x32x16_bf16 v[112:127], v[220:223], v[132:135], v[112:127]
	ds_read_b128 v[220:223], v168 offset:13856
	v_lshl_add_u64 v[236:237], v[176:177], 0, s[6:7]
	global_load_dwordx4 v[164:167], v[236:237], off
	s_waitcnt lgkmcnt(7)
	v_mfma_f32_32x32x16_bf16 v[112:127], v[224:227], v[136:139], v[112:127]
	ds_read_b128 v[224:227], v168 offset:18464
	s_waitcnt lgkmcnt(7)
	v_mfma_f32_32x32x16_bf16 v[112:127], v[228:231], v[140:143], v[112:127]
	ds_read_b128 v[228:231], v168 offset:23072
	s_setprio 0
; #define MFMA32(a, b, c) __builtin_amdgcn_mfma_f32_32x32x16_bf16((a), (b), (c), 0, 0, 0)
; DI float xmax32(float x) { auto t = __builtin_amdgcn_permlane32_swap(__float_as_uint(x), __float_as_uint(x), false, false); return fmaxf(__uint_as_float(t[0]), __uint_as_float(t[1])); }
; template <int DK, int DV>
; DI void attn_map(f32x16 (&O)[DV / 32], float& lsum, const u16* qrow, const u16* K1, int ldk1, const u16* K2, int ldk2, const u16* Vt, int nkeys, char* smem) {
;     ...
;     f32x16 s[2];
;     __builtin_amdgcn_s_setprio(1);
; #pragma unroll
;     for (int j = 0; j < 2; ++j) {
; #pragma unroll
;       for (int ks = 0; ks < DK / 16; ++ks) {
;         bf16x8 kf = *(const bf16x8*)(Ks + (j * 32 + r) * KST + ks * 16 + 8 * h);
;         s[j] = (ks == 0) ? MFMA32(kf, qf[ks], negm) : MFMA32(kf, qf[ks], s[j]);
;       }
;     }
;     {
;       constexpr int NQK = 2 * (DK / 16);
;       __builtin_amdgcn_sched_group_barrier(0x100, 2, 0);
; #pragma unroll
;       for (int q = 0; q < NQK - 2; ++q) { __builtin_amdgcn_sched_group_barrier(0x008, 1, 0); __builtin_amdgcn_sched_group_barrier(0x100, 1, 0); }
;       __builtin_amdgcn_sched_group_barrier(0x008, 2, 0);
;     }
;     ...
;     float mx0 = fmaxf(fmaxf(s[0][0], s[0][1]), s[0][2]), mx1 = fmaxf(fmaxf(s[1][0], s[1][1]), s[1][2]);
; #pragma unroll
;     for (int i = 3; i < 15; i += 2) { mx0 = fmaxf(fmaxf(mx0, s[0][i]), s[0][i + 1]); mx1 = fmaxf(fmaxf(mx1, s[1][i]), s[1][i + 1]); }
;     float mx = fmaxf(fmaxf(mx0, mx1), fmaxf(s[0][15], s[1][15]));
;     mx = xmax32(mx);
;     const bool first = (k0 == 0);
;     if (first || __any(mx > 6.f)) {
;       float dl = first ? mx : fmaxf(mx, 0.f);
;       float alpha = __builtin_amdgcn_exp2f(-dl);
; #pragma unroll
;       for (int i = 0; i < 16; ++i) { negm[i] -= dl; lacc[i] *= alpha; }
; #pragma unroll
;       for (int dd = 0; dd < DV / 32; ++dd)
; #pragma unroll
;         for (int i = 0; i < 16; ++i) O[dd][i] *= alpha;
; #pragma unroll
;       for (int j = 0; j < 2; ++j)
; #pragma unroll
;         for (int i = 0; i < 16; ++i) s[j][i] -= dl;
;     }
.Lqk_join_A:
	s_nop 0
	v_max3_f32 v194, v96, v97, v98
	s_nop 8
	v_max3_f32 v195, v112, v113, v114
	v_max3_f32 v194, v194, v99, v100
	v_max3_f32 v195, v195, v115, v116
	v_max3_f32 v194, v194, v101, v102
	v_max3_f32 v195, v195, v117, v118
	v_max3_f32 v194, v194, v103, v104
	v_max3_f32 v195, v195, v119, v120
	v_max3_f32 v194, v194, v105, v106
	v_max3_f32 v195, v195, v121, v122
	v_max3_f32 v194, v194, v107, v108
	v_max3_f32 v195, v195, v123, v124
	v_max_f32_e32 v196, v127, v127
	v_max_f32_e32 v197, v111, v111
	v_max3_f32 v194, v194, v109, v110
	v_max3_f32 v195, v195, v125, v126
	v_max_f32_e32 v196, v197, v196
	v_max3_f32 v194, v194, v195, v196
	v_mov_b32_e32 v195, v194
	s_nop 1
	v_permlane32_swap_b32_e32 v194, v195
	v_max_f32_e32 v195, v195, v195
	v_max_f32_e32 v194, v194, v194
	v_max_f32_e32 v194, v194, v195
	v_cmp_lt_f32_e32 vcc, s45, v194
	s_cbranch_vccz .LBB0_381
	v_max_f32_e32 v194, v194, v194
	v_max_f32_e32 v195, 0, v194
	v_exp_f32_e64 v194, -v195
	v_sub_f32_e32 v31, v31, v195
	v_sub_f32_e32 v30, v30, v195
	v_sub_f32_e32 v29, v29, v195
	v_pk_mul_f32 v[62:63], v[62:63], v[194:195] op_sel_hi:[1,0]
	v_pk_mul_f32 v[60:61], v[60:61], v[194:195] op_sel_hi:[1,0]
	v_pk_mul_f32 v[58:59], v[58:59], v[194:195] op_sel_hi:[1,0]
	v_pk_mul_f32 v[56:57], v[56:57], v[194:195] op_sel_hi:[1,0]
	v_pk_mul_f32 v[54:55], v[54:55], v[194:195] op_sel_hi:[1,0]
	v_pk_mul_f32 v[52:53], v[52:53], v[194:195] op_sel_hi:[1,0]
	v_pk_mul_f32 v[50:51], v[50:51], v[194:195] op_sel_hi:[1,0]
	v_pk_mul_f32 v[48:49], v[48:49], v[194:195] op_sel_hi:[1,0]
	v_pk_mul_f32 v[46:47], v[46:47], v[194:195] op_sel_hi:[1,0]
	v_pk_mul_f32 v[44:45], v[44:45], v[194:195] op_sel_hi:[1,0]
	v_pk_mul_f32 v[42:43], v[42:43], v[194:195] op_sel_hi:[1,0]
	v_pk_mul_f32 v[40:41], v[40:41], v[194:195] op_sel_hi:[1,0]
	v_pk_mul_f32 v[38:39], v[38:39], v[194:195] op_sel_hi:[1,0]
	v_pk_mul_f32 v[36:37], v[36:37], v[194:195] op_sel_hi:[1,0]
	v_pk_mul_f32 v[34:35], v[34:35], v[194:195] op_sel_hi:[1,0]
	v_pk_mul_f32 v[32:33], v[32:33], v[194:195] op_sel_hi:[1,0]
	v_pk_mul_f32 v[78:79], v[78:79], v[194:195] op_sel_hi:[1,0]
	v_pk_mul_f32 v[76:77], v[76:77], v[194:195] op_sel_hi:[1,0]
	v_pk_mul_f32 v[74:75], v[74:75], v[194:195] op_sel_hi:[1,0]
	v_pk_mul_f32 v[72:73], v[72:73], v[194:195] op_sel_hi:[1,0]
	v_pk_mul_f32 v[70:71], v[70:71], v[194:195] op_sel_hi:[1,0]
	v_pk_mul_f32 v[68:69], v[68:69], v[194:195] op_sel_hi:[1,0]
	v_pk_mul_f32 v[66:67], v[66:67], v[194:195] op_sel_hi:[1,0]
	v_pk_mul_f32 v[64:65], v[64:65], v[194:195] op_sel_hi:[1,0]
	v_pk_mul_f32 v[94:95], v[94:95], v[194:195] op_sel_hi:[1,0]
	v_pk_mul_f32 v[92:93], v[92:93], v[194:195] op_sel_hi:[1,0]
	v_pk_mul_f32 v[90:91], v[90:91], v[194:195] op_sel_hi:[1,0]
	v_pk_mul_f32 v[88:89], v[88:89], v[194:195] op_sel_hi:[1,0]
	v_pk_mul_f32 v[86:87], v[86:87], v[194:195] op_sel_hi:[1,0]
	v_pk_mul_f32 v[84:85], v[84:85], v[194:195] op_sel_hi:[1,0]
	v_pk_mul_f32 v[82:83], v[82:83], v[194:195] op_sel_hi:[1,0]
	v_pk_mul_f32 v[80:81], v[80:81], v[194:195] op_sel_hi:[1,0]
	v_sub_f32_e32 v28, v28, v195
	v_sub_f32_e32 v27, v27, v195
	v_sub_f32_e32 v26, v26, v195
	v_sub_f32_e32 v25, v25, v195
	v_sub_f32_e32 v24, v24, v195
	v_sub_f32_e32 v23, v23, v195
	v_sub_f32_e32 v22, v22, v195
	v_sub_f32_e32 v21, v21, v195
	v_sub_f32_e32 v20, v20, v195
	v_sub_f32_e32 v19, v19, v195
	v_sub_f32_e32 v18, v18, v195
	v_sub_f32_e32 v17, v17, v195
	v_sub_f32_e32 v16, v16, v195
	v_sub_f32_e32 v96, v96, v195
	v_sub_f32_e32 v97, v97, v195
	v_sub_f32_e32 v98, v98, v195
	v_sub_f32_e32 v99, v99, v195
	v_sub_f32_e32 v100, v100, v195
	v_sub_f32_e32 v101, v101, v195
	v_sub_f32_e32 v102, v102, v195
	v_sub_f32_e32 v103, v103, v195
	v_sub_f32_e32 v104, v104, v195
	v_sub_f32_e32 v105, v105, v195
	v_sub_f32_e32 v106, v106, v195
	v_sub_f32_e32 v107, v107, v195
	v_sub_f32_e32 v108, v108, v195
	v_sub_f32_e32 v109, v109, v195
	v_sub_f32_e32 v110, v110, v195
	v_sub_f32_e32 v111, v111, v195
	v_sub_f32_e32 v112, v112, v195
	v_sub_f32_e32 v113, v113, v195
	v_sub_f32_e32 v114, v114, v195
	v_sub_f32_e32 v115, v115, v195
	v_sub_f32_e32 v116, v116, v195
	v_sub_f32_e32 v117, v117, v195
	v_sub_f32_e32 v118, v118, v195
	v_sub_f32_e32 v119, v119, v195
	v_sub_f32_e32 v120, v120, v195
	v_sub_f32_e32 v121, v121, v195
	v_sub_f32_e32 v122, v122, v195
	v_sub_f32_e32 v123, v123, v195
	v_sub_f32_e32 v124, v124, v195
	v_sub_f32_e32 v125, v125, v195
	v_sub_f32_e32 v126, v126, v195
	v_sub_f32_e32 v127, v127, v195
	v_pk_mul_f32 v[14:15], v[14:15], v[194:195] op_sel_hi:[1,0]
	v_pk_mul_f32 v[12:13], v[12:13], v[194:195] op_sel_hi:[1,0]
	v_pk_mul_f32 v[10:11], v[10:11], v[194:195] op_sel_hi:[1,0]
	v_pk_mul_f32 v[8:9], v[8:9], v[194:195] op_sel_hi:[1,0]
	v_pk_mul_f32 v[6:7], v[6:7], v[194:195] op_sel_hi:[1,0]
	v_pk_mul_f32 v[4:5], v[4:5], v[194:195] op_sel_hi:[1,0]
	v_pk_mul_f32 v[2:3], v[2:3], v[194:195] op_sel_hi:[1,0]
	v_pk_mul_f32 v[0:1], v[0:1], v[194:195] op_sel_hi:[1,0]
	s_branch .LBB0_381
.Lqk_last_A:
	s_setprio 1
	ds_read_b128 v[200:203], v168
	ds_read_b128 v[204:207], v168 offset:32
	ds_read_b128 v[208:211], v168 offset:64
	ds_read_b128 v[212:215], v168 offset:96
	ds_read_b128 v[216:219], v168 offset:4608
	ds_read_b128 v[220:223], v168 offset:4640
	ds_read_b128 v[224:227], v168 offset:4672
	ds_read_b128 v[228:231], v168 offset:4704
	s_waitcnt lgkmcnt(7)
	v_mfma_f32_32x32x16_bf16 v[96:111], v[200:203], v[128:131], v[16:31]
	ds_read_b128 v[200:203], v168 offset:9216
	s_waitcnt lgkmcnt(7)
	v_mfma_f32_32x32x16_bf16 v[96:111], v[204:207], v[132:135], v[96:111]
	ds_read_b128 v[204:207], v168 offset:13824
	s_waitcnt lgkmcnt(7)
	v_mfma_f32_32x32x16_bf16 v[96:111], v[208:211], v[136:139], v[96:111]
	ds_read_b128 v[208:211], v168 offset:18432
	s_waitcnt lgkmcnt(7)
	v_mfma_f32_32x32x16_bf16 v[96:111], v[212:215], v[140:143], v[96:111]
	ds_read_b128 v[212:215], v168 offset:23040
	s_waitcnt lgkmcnt(7)
	v_mfma_f32_32x32x16_bf16 v[112:127], v[216:219], v[128:131], v[16:31]
	ds_read_b128 v[216:219], v168 offset:9248
	s_waitcnt lgkmcnt(7)
	v_mfma_f32_32x32x16_bf16 v[112:127], v[220:223], v[132:135], v[112:127]
	ds_read_b128 v[220:223], v168 offset:13856
	s_waitcnt lgkmcnt(7)
	v_mfma_f32_32x32x16_bf16 v[112:127], v[224:227], v[136:139], v[112:127]
	ds_read_b128 v[224:227], v168 offset:18464
	s_waitcnt lgkmcnt(7)
	v_mfma_f32_32x32x16_bf16 v[112:127], v[228:231], v[140:143], v[112:127]
	ds_read_b128 v[228:231], v168 offset:23072
	s_setprio 0
	s_branch .Lqk_join_A

; #define MFMA32(a, b, c) __builtin_amdgcn_mfma_f32_32x32x16_bf16((a), (b), (c), 0, 0, 0)
; template <int DK, int DV>
; DI void attn_map(f32x16 (&O)[DV / 32], float& lsum, const u16* qrow, const u16* K1, int ldk1, const u16* K2, int ldk2, const u16* Vt, int nkeys, char* smem) {
;     ...
;   for (int k0 = 0; k0 < nkeys; k0 += 64) {
;     __syncthreads();
; #pragma unroll
;     for (int i = 0; i < NKR; ++i) { int id = tid + i * 256; int row = id / KCH, cc = id - row * KCH; *(u32x4*)(Ks + row * KST + cc * 8) = kreg[i]; }
; #pragma unroll
;     for (int i = 0; i < NVR; ++i) {
;       int id = tid + i * 256; int row = id >> 3, cc = id & 7;
;       u16* base = Vs + row * VST + (cc >> 1) * 16 + (cc & 1) * 4;
;       u32x2 t0 = {vreg[i].x, vreg[i].y}, t1 = {vreg[i].z, vreg[i].w};
;       *(u32x2*)base = t0; *(u32x2*)(base + 8) = t1;
;     }
;     __syncthreads();
;     if (k0 + 64 < nkeys) ATT_LOAD(k0 + 64)
;     f32x16 s[2];
;     __builtin_amdgcn_s_setprio(1);
; #pragma unroll
;     for (int j = 0; j < 2; ++j) {
; #pragma unroll
;       for (int ks = 0; ks < DK / 16; ++ks) {
;         bf16x8 kf = *(const bf16x8*)(Ks + (j * 32 + r) * KST + ks * 16 + 8 * h);
;         s[j] = (ks == 0) ? MFMA32(kf, qf[ks], negm) : MFMA32(kf, qf[ks], s[j]);
;       }
;     }
;     {
;       constexpr int NQK = 2 * (DK / 16);
;       __builtin_amdgcn_sched_group_barrier(0x100, 2, 0);
; #pragma unroll
;       for (int q = 0; q < NQK - 2; ++q) { __builtin_amdgcn_sched_group_barrier(0x008, 1, 0); __builtin_amdgcn_sched_group_barrier(0x100, 1, 0); }
;       __builtin_amdgcn_sched_group_barrier(0x008, 2, 0);
;     }
;     __builtin_amdgcn_s_setprio(0);
.LBB0_404:
	s_cmpk_gt_u32 s10, 0x10bf
	s_cselect_b64 s[6:7], -1, 0
	s_and_b64 vcc, exec, s[6:7]
	s_barrier
	s_waitcnt vmcnt(5)
	ds_write_b128 v189, v[144:147]
	s_waitcnt vmcnt(4)
	ds_write_b128 v190, v[148:151]
	s_waitcnt vmcnt(3)
	ds_write2_b64 v191, v[152:153], v[154:155] offset0:128 offset1:130
	s_waitcnt vmcnt(2)
	ds_write2_b64 v192, v[156:157], v[158:159] offset0:128 offset1:130
	s_waitcnt vmcnt(1)
	ds_write2_b64 v193, v[160:161], v[162:163] offset0:128 offset1:130
	s_waitcnt vmcnt(0)
	ds_write2_b64 v194, v[164:165], v[166:167] offset0:128 offset1:130
	s_waitcnt lgkmcnt(0)
	s_barrier
	s_cbranch_vccnz .Lqk_last_B
	s_setprio 1
	ds_read_b128 v[200:203], v195
	ds_read_b128 v[204:207], v195 offset:32
	ds_read_b128 v[208:211], v195 offset:64
	ds_read_b128 v[212:215], v195 offset:96
	ds_read_b128 v[216:219], v195 offset:4608
	ds_read_b128 v[220:223], v195 offset:4640
	ds_read_b128 v[224:227], v195 offset:4672
	ds_read_b128 v[228:231], v195 offset:4704
	s_waitcnt lgkmcnt(7)
	v_mfma_f32_32x32x16_bf16 v[96:111], v[200:203], v[128:131], v[80:95]
	ds_read_b128 v[200:203], v195 offset:9216
	v_lshl_add_u64 v[236:237], v[182:183], 0, v[168:169]
	global_load_dwordx4 v[144:147], v[186:187], off
	s_waitcnt lgkmcnt(7)
	v_mfma_f32_32x32x16_bf16 v[96:111], v[204:207], v[132:135], v[96:111]
	ds_read_b128 v[204:207], v195 offset:13824
	global_load_dwordx4 v[148:151], v[184:185], off
	global_load_dwordx4 v[152:155], v[236:237], off
	s_waitcnt lgkmcnt(7)
	v_mfma_f32_32x32x16_bf16 v[96:111], v[208:211], v[136:139], v[96:111]
	ds_read_b128 v[208:211], v195 offset:18432
	v_lshl_add_u64 v[236:237], v[180:181], 0, v[168:169]
	global_load_dwordx4 v[156:159], v[236:237], off
	s_waitcnt lgkmcnt(7)
	v_mfma_f32_32x32x16_bf16 v[96:111], v[212:215], v[140:143], v[96:111]
	ds_read_b128 v[212:215], v195 offset:23040
	v_lshl_add_u64 v[236:237], v[178:179], 0, v[168:169]
	global_load_dwordx4 v[160:163], v[236:237], off
	s_waitcnt lgkmcnt(7)
	v_mfma_f32_32x32x16_bf16 v[112:127], v[216:219], v[128:131], v[80:95]
	ds_read_b128 v[216:219], v195 offset:9248
	v_lshl_add_u64 v[236:237], v[176:177], 0, v[168:169]
	global_load_dwordx4 v[164:167], v[236:237], off
	s_waitcnt lgkmcnt(7)
	v_mfma_f32_32x32x16_bf16 v[112:127], v[220:223], v[132:135], v[112:127]
	ds_read_b128 v[220:223], v195 offset:13856
	s_waitcnt lgkmcnt(7)
	v_mfma_f32_32x32x16_bf16 v[112:127], v[224:227], v[136:139], v[112:127]
	ds_read_b128 v[224:227], v195 offset:18464
	s_waitcnt lgkmcnt(7)
	v_mfma_f32_32x32x16_bf16 v[112:127], v[228:231], v[140:143], v[112:127]
	ds_read_b128 v[228:231], v195 offset:23072
	s_setprio 0
; #define MFMA32(a, b, c) __builtin_amdgcn_mfma_f32_32x32x16_bf16((a), (b), (c), 0, 0, 0)
; DI float xmax32(float x) { auto t = __builtin_amdgcn_permlane32_swap(__float_as_uint(x), __float_as_uint(x), false, false); return fmaxf(__uint_as_float(t[0]), __uint_as_float(t[1])); }
; template <int DK, int DV>
; DI void attn_map(f32x16 (&O)[DV / 32], float& lsum, const u16* qrow, const u16* K1, int ldk1, const u16* K2, int ldk2, const u16* Vt, int nkeys, char* smem) {
;     ...
;     f32x16 s[2];
;     __builtin_amdgcn_s_setprio(1);
; #pragma unroll
;     for (int j = 0; j < 2; ++j) {
; #pragma unroll
;       for (int ks = 0; ks < DK / 16; ++ks) {
;         bf16x8 kf = *(const bf16x8*)(Ks + (j * 32 + r) * KST + ks * 16 + 8 * h);
;         s[j] = (ks == 0) ? MFMA32(kf, qf[ks], negm) : MFMA32(kf, qf[ks], s[j]);
;       }
;     }
;     {
;       constexpr int NQK = 2 * (DK / 16);
;       __builtin_amdgcn_sched_group_barrier(0x100, 2, 0);
; #pragma unroll
;       for (int q = 0; q < NQK - 2; ++q) { __builtin_amdgcn_sched_group_barrier(0x008, 1, 0); __builtin_amdgcn_sched_group_barrier(0x100, 1, 0); }
;       __builtin_amdgcn_sched_group_barrier(0x008, 2, 0);
;     }
;     ...
;     float mx0 = fmaxf(fmaxf(s[0][0], s[0][1]), s[0][2]), mx1 = fmaxf(fmaxf(s[1][0], s[1][1]), s[1][2]);
; #pragma unroll
;     for (int i = 3; i < 15; i += 2) { mx0 = fmaxf(fmaxf(mx0, s[0][i]), s[0][i + 1]); mx1 = fmaxf(fmaxf(mx1, s[1][i]), s[1][i + 1]); }
;     float mx = fmaxf(fmaxf(mx0, mx1), fmaxf(s[0][15], s[1][15]));
;     mx = xmax32(mx);
;     const bool first = (k0 == 0);
;     if (first || __any(mx > 6.f)) {
;       float dl = first ? mx : fmaxf(mx, 0.f);
;       float alpha = __builtin_amdgcn_exp2f(-dl);
; #pragma unroll
;       for (int i = 0; i < 16; ++i) { negm[i] -= dl; lacc[i] *= alpha; }
; #pragma unroll
;       for (int dd = 0; dd < DV / 32; ++dd)
; #pragma unroll
;         for (int i = 0; i < 16; ++i) O[dd][i] *= alpha;
; #pragma unroll
;       for (int j = 0; j < 2; ++j)
; #pragma unroll
;         for (int i = 0; i < 16; ++i) s[j][i] -= dl;
;     }
.Lqk_join_B:
	s_nop 0
	v_max3_f32 v196, v96, v97, v98
	s_nop 8
	v_max3_f32 v197, v112, v113, v114
	v_max3_f32 v196, v196, v99, v100
	v_max3_f32 v197, v197, v115, v116
	v_max3_f32 v196, v196, v101, v102
	v_max3_f32 v197, v197, v117, v118
	v_max3_f32 v196, v196, v103, v104
	v_max3_f32 v197, v197, v119, v120
	v_max3_f32 v196, v196, v105, v106
	v_max3_f32 v197, v197, v121, v122
	v_max3_f32 v196, v196, v107, v108
	v_max3_f32 v197, v197, v123, v124
	v_max_f32_e32 v198, v127, v127
	v_max_f32_e32 v199, v111, v111
	v_max3_f32 v196, v196, v109, v110
	v_max3_f32 v197, v197, v125, v126
	v_max_f32_e32 v198, v199, v198
	v_max3_f32 v196, v196, v197, v198
	v_mov_b32_e32 v197, v196
	s_nop 1
	v_permlane32_swap_b32_e32 v196, v197
	v_max_f32_e32 v197, v197, v197
	v_max_f32_e32 v196, v196, v196
	v_max_f32_e32 v196, v196, v197
	v_cmp_lt_f32_e32 vcc, s45, v196
	s_cbranch_vccz .LBB0_403
	v_max_f32_e32 v196, v196, v196
	v_max_f32_e32 v197, 0, v196
	v_exp_f32_e64 v196, -v197
	v_sub_f32_e32 v95, v95, v197
	v_sub_f32_e32 v94, v94, v197
	v_sub_f32_e32 v93, v93, v197
	v_pk_mul_f32 v[62:63], v[62:63], v[196:197] op_sel_hi:[1,0]
	v_pk_mul_f32 v[60:61], v[60:61], v[196:197] op_sel_hi:[1,0]
	v_pk_mul_f32 v[58:59], v[58:59], v[196:197] op_sel_hi:[1,0]
	v_pk_mul_f32 v[56:57], v[56:57], v[196:197] op_sel_hi:[1,0]
	v_pk_mul_f32 v[54:55], v[54:55], v[196:197] op_sel_hi:[1,0]
	v_pk_mul_f32 v[52:53], v[52:53], v[196:197] op_sel_hi:[1,0]
	v_pk_mul_f32 v[50:51], v[50:51], v[196:197] op_sel_hi:[1,0]
	v_pk_mul_f32 v[48:49], v[48:49], v[196:197] op_sel_hi:[1,0]
	v_pk_mul_f32 v[46:47], v[46:47], v[196:197] op_sel_hi:[1,0]
	v_pk_mul_f32 v[44:45], v[44:45], v[196:197] op_sel_hi:[1,0]
	v_pk_mul_f32 v[42:43], v[42:43], v[196:197] op_sel_hi:[1,0]
	v_pk_mul_f32 v[40:41], v[40:41], v[196:197] op_sel_hi:[1,0]
	v_pk_mul_f32 v[38:39], v[38:39], v[196:197] op_sel_hi:[1,0]
	v_pk_mul_f32 v[36:37], v[36:37], v[196:197] op_sel_hi:[1,0]
	v_pk_mul_f32 v[34:35], v[34:35], v[196:197] op_sel_hi:[1,0]
	v_pk_mul_f32 v[32:33], v[32:33], v[196:197] op_sel_hi:[1,0]
	v_pk_mul_f32 v[30:31], v[30:31], v[196:197] op_sel_hi:[1,0]
	v_pk_mul_f32 v[28:29], v[28:29], v[196:197] op_sel_hi:[1,0]
	v_pk_mul_f32 v[26:27], v[26:27], v[196:197] op_sel_hi:[1,0]
	v_pk_mul_f32 v[24:25], v[24:25], v[196:197] op_sel_hi:[1,0]
	v_pk_mul_f32 v[22:23], v[22:23], v[196:197] op_sel_hi:[1,0]
	v_pk_mul_f32 v[20:21], v[20:21], v[196:197] op_sel_hi:[1,0]
	v_pk_mul_f32 v[18:19], v[18:19], v[196:197] op_sel_hi:[1,0]
	v_pk_mul_f32 v[16:17], v[16:17], v[196:197] op_sel_hi:[1,0]
	v_pk_mul_f32 v[14:15], v[14:15], v[196:197] op_sel_hi:[1,0]
	v_pk_mul_f32 v[12:13], v[12:13], v[196:197] op_sel_hi:[1,0]
	v_pk_mul_f32 v[10:11], v[10:11], v[196:197] op_sel_hi:[1,0]
	v_pk_mul_f32 v[8:9], v[8:9], v[196:197] op_sel_hi:[1,0]
	v_pk_mul_f32 v[6:7], v[6:7], v[196:197] op_sel_hi:[1,0]
	v_pk_mul_f32 v[4:5], v[4:5], v[196:197] op_sel_hi:[1,0]
	v_pk_mul_f32 v[2:3], v[2:3], v[196:197] op_sel_hi:[1,0]
	v_pk_mul_f32 v[0:1], v[0:1], v[196:197] op_sel_hi:[1,0]
	v_sub_f32_e32 v92, v92, v197
	v_sub_f32_e32 v91, v91, v197
	v_sub_f32_e32 v90, v90, v197
	v_sub_f32_e32 v89, v89, v197
	v_sub_f32_e32 v88, v88, v197
	v_sub_f32_e32 v87, v87, v197
	v_sub_f32_e32 v86, v86, v197
	v_sub_f32_e32 v85, v85, v197
	v_sub_f32_e32 v84, v84, v197
	v_sub_f32_e32 v83, v83, v197
	v_sub_f32_e32 v82, v82, v197
	v_sub_f32_e32 v81, v81, v197
	v_sub_f32_e32 v80, v80, v197
	v_sub_f32_e32 v96, v96, v197
	v_sub_f32_e32 v97, v97, v197
	v_sub_f32_e32 v98, v98, v197
	v_sub_f32_e32 v99, v99, v197
	v_sub_f32_e32 v100, v100, v197
	v_sub_f32_e32 v101, v101, v197
	v_sub_f32_e32 v102, v102, v197
	v_sub_f32_e32 v103, v103, v197
	v_sub_f32_e32 v104, v104, v197
	v_sub_f32_e32 v105, v105, v197
	v_sub_f32_e32 v106, v106, v197
	v_sub_f32_e32 v107, v107, v197
	v_sub_f32_e32 v108, v108, v197
	v_sub_f32_e32 v109, v109, v197
	v_sub_f32_e32 v110, v110, v197
	v_sub_f32_e32 v111, v111, v197
	v_sub_f32_e32 v112, v112, v197
	v_sub_f32_e32 v113, v113, v197
	v_sub_f32_e32 v114, v114, v197
	v_sub_f32_e32 v115, v115, v197
	v_sub_f32_e32 v116, v116, v197
	v_sub_f32_e32 v117, v117, v197
	v_sub_f32_e32 v118, v118, v197
	v_sub_f32_e32 v119, v119, v197
	v_sub_f32_e32 v120, v120, v197
	v_sub_f32_e32 v121, v121, v197
	v_sub_f32_e32 v122, v122, v197
	v_sub_f32_e32 v123, v123, v197
	v_sub_f32_e32 v124, v124, v197
	v_sub_f32_e32 v125, v125, v197
	v_sub_f32_e32 v126, v126, v197
	v_sub_f32_e32 v127, v127, v197
	v_pk_mul_f32 v[78:79], v[78:79], v[196:197] op_sel_hi:[1,0]
	v_pk_mul_f32 v[76:77], v[76:77], v[196:197] op_sel_hi:[1,0]
	v_pk_mul_f32 v[74:75], v[74:75], v[196:197] op_sel_hi:[1,0]
	v_pk_mul_f32 v[72:73], v[72:73], v[196:197] op_sel_hi:[1,0]
	v_pk_mul_f32 v[70:71], v[70:71], v[196:197] op_sel_hi:[1,0]
	v_pk_mul_f32 v[68:69], v[68:69], v[196:197] op_sel_hi:[1,0]
	v_pk_mul_f32 v[66:67], v[66:67], v[196:197] op_sel_hi:[1,0]
	v_pk_mul_f32 v[64:65], v[64:65], v[196:197] op_sel_hi:[1,0]
	s_branch .LBB0_403
.Lqk_last_B:
	s_setprio 1
	ds_read_b128 v[200:203], v195
	ds_read_b128 v[204:207], v195 offset:32
	ds_read_b128 v[208:211], v195 offset:64
	ds_read_b128 v[212:215], v195 offset:96
	ds_read_b128 v[216:219], v195 offset:4608
	ds_read_b128 v[220:223], v195 offset:4640
	ds_read_b128 v[224:227], v195 offset:4672
	ds_read_b128 v[228:231], v195 offset:4704
	s_waitcnt lgkmcnt(7)
	v_mfma_f32_32x32x16_bf16 v[96:111], v[200:203], v[128:131], v[80:95]
	ds_read_b128 v[200:203], v195 offset:9216
	s_waitcnt lgkmcnt(7)
	v_mfma_f32_32x32x16_bf16 v[96:111], v[204:207], v[132:135], v[96:111]
	ds_read_b128 v[204:207], v195 offset:13824
	s_waitcnt lgkmcnt(7)
	v_mfma_f32_32x32x16_bf16 v[96:111], v[208:211], v[136:139], v[96:111]
	ds_read_b128 v[208:211], v195 offset:18432
	s_waitcnt lgkmcnt(7)
	v_mfma_f32_32x32x16_bf16 v[96:111], v[212:215], v[140:143], v[96:111]
	ds_read_b128 v[212:215], v195 offset:23040
	s_waitcnt lgkmcnt(7)
	v_mfma_f32_32x32x16_bf16 v[112:127], v[216:219], v[128:131], v[80:95]
	ds_read_b128 v[216:219], v195 offset:9248
	s_waitcnt lgkmcnt(7)
	v_mfma_f32_32x32x16_bf16 v[112:127], v[220:223], v[132:135], v[112:127]
	ds_read_b128 v[220:223], v195 offset:13856
	s_waitcnt lgkmcnt(7)
	v_mfma_f32_32x32x16_bf16 v[112:127], v[224:227], v[136:139], v[112:127]
	ds_read_b128 v[224:227], v195 offset:18464
	s_waitcnt lgkmcnt(7)
	v_mfma_f32_32x32x16_bf16 v[112:127], v[228:231], v[140:143], v[112:127]
	ds_read_b128 v[228:231], v195 offset:23072
	s_setprio 0
	s_branch .Lqk_join_B

; template <int DK, int DV>
; DI void attn_map(f32x16 (&O)[DV / 32], float& lsum, const u16* qrow, const u16* K1, int ldk1, const u16* K2, int ldk2, const u16* Vt, int nkeys, char* smem) {
;     ...
;   for (int k0 = 0; k0 < nkeys; k0 += 64) {
;     __syncthreads();
; #pragma unroll
;     for (int i = 0; i < NKR; ++i) { int id = tid + i * 256; int row = id / KCH, cc = id - row * KCH; *(u32x4*)(Ks + row * KST + cc * 8) = kreg[i]; }
; #pragma unroll
;     for (int i = 0; i < NVR; ++i) {
;       int id = tid + i * 256; int row = id >> 3, cc = id & 7;
;       u16* base = Vs + row * VST + (cc >> 1) * 16 + (cc & 1) * 4;
;       u32x2 t0 = {vreg[i].x, vreg[i].y}, t1 = {vreg[i].z, vreg[i].w};
;       *(u32x2*)base = t0; *(u32x2*)(base + 8) = t1;
;     }
;     __syncthreads();
;     if (k0 + 64 < nkeys) ATT_LOAD(k0 + 64)
;     f32x16 s[2];
;     __builtin_amdgcn_s_setprio(1);
; #pragma unroll
;     for (int j = 0; j < 2; ++j) {
; #pragma unroll
;       for (int ks = 0; ks < DK / 16; ++ks) {
;         bf16x8 kf = *(const bf16x8*)(Ks + (j * 32 + r) * KST + ks * 16 + 8 * h);
;         s[j] = (ks == 0) ? MFMA32(kf, qf[ks], negm) : MFMA32(kf, qf[ks], s[j]);
;       }
;     }
;     {
;       constexpr int NQK = 2 * (DK / 16);
;       __builtin_amdgcn_sched_group_barrier(0x100, 2, 0);
; #pragma unroll
;       for (int q = 0; q < NQK - 2; ++q) { __builtin_amdgcn_sched_group_barrier(0x008, 1, 0); __builtin_amdgcn_sched_group_barrier(0x100, 1, 0); }
;       __builtin_amdgcn_sched_group_barrier(0x008, 2, 0);
;     }
;     __builtin_amdgcn_s_setprio(0);
;     float mx0 = fmaxf(fmaxf(s[0][0], s[0][1]), s[0][2]), mx1 = fmaxf(fmaxf(s[1][0], s[1][1]), s[1][2]);
; #pragma unroll
;     for (int i = 3; i < 15; i += 2) { mx0 = fmaxf(fmaxf(mx0, s[0][i]), s[0][i + 1]); mx1 = fmaxf(fmaxf(mx1, s[1][i]), s[1][i + 1]); }
;     float mx = fmaxf(fmaxf(mx0, mx1), fmaxf(s[0][15], s[1][15]));
;     mx = xmax32(mx);
;     const bool first = (k0 == 0);
;     if (first || __any(mx > 6.f)) {
;       float dl = first ? mx : fmaxf(mx, 0.f);
;       float alpha = __builtin_amdgcn_exp2f(-dl);
; #pragma unroll
;       for (int i = 0; i < 16; ++i) { negm[i] -= dl; lacc[i] *= alpha; }
; #pragma unroll
;       for (int dd = 0; dd < DV / 32; ++dd)
; #pragma unroll
;         for (int i = 0; i < 16; ++i) O[dd][i] *= alpha;
; #pragma unroll
;       for (int j = 0; j < 2; ++j)
; #pragma unroll
.LBB0_436:
	s_add_u32 s6, s10, 64
	s_addc_u32 s7, s11, 0
	s_cmpk_gt_u32 s6, 0x10bf
	s_cselect_b64 s[8:9], -1, 0
	s_and_b64 vcc, exec, s[8:9]
	s_barrier
	s_waitcnt vmcnt(4)
	ds_write_b128 v149, v[120:123]
	s_waitcnt vmcnt(3)
	ds_write_b128 v164, v[124:127]
	s_waitcnt vmcnt(2)
	ds_write_b128 v165, v[128:131]
	s_waitcnt vmcnt(1)
	ds_write2_b64 v166, v[132:133], v[134:135] offset0:128 offset1:130
	s_waitcnt vmcnt(0)
	ds_write2_b64 v167, v[136:137], v[138:139] offset0:128 offset1:130
	s_waitcnt lgkmcnt(0)
	s_barrier
	s_cbranch_vccnz .Lqk_last_C
	s_setprio 1
	ds_read_b128 v[190:193], v143
	ds_read_b128 v[194:197], v143 offset:32
	ds_read_b128 v[198:201], v143 offset:64
	ds_read_b128 v[202:205], v143 offset:96
	ds_read_b128 v[206:209], v143 offset:128
	ds_read_b128 v[210:213], v143 offset:160
	ds_read_b128 v[214:217], v143 offset:6656
	ds_read_b128 v[218:221], v143 offset:6688
	ds_read_b128 v[222:225], v143 offset:6720
	ds_read_b128 v[226:229], v143 offset:6752
	ds_read_b128 v[230:233], v143 offset:6784
	ds_read_b128 v[234:237], v143 offset:6816
	s_waitcnt lgkmcnt(11)
	v_mfma_f32_32x32x16_bf16 v[64:79], v[190:193], v[96:99], v[16:31]
	ds_read_b128 v[190:193], v168 offset:13312
	v_lshl_add_u64 v[188:189], v[162:163], 0, s[10:11]
	v_lshlrev_b64 v[188:189], v144, v[188:189]
	s_waitcnt lgkmcnt(11)
	v_mfma_f32_32x32x16_bf16 v[64:79], v[194:197], v[100:103], v[64:79]
	ds_read_b128 v[194:197], v168 offset:17920
	v_lshl_add_u64 v[188:189], v[146:147], 0, v[188:189]
	global_load_dwordx4 v[120:123], v[188:189], off
	s_waitcnt lgkmcnt(11)
	v_mfma_f32_32x32x16_bf16 v[64:79], v[198:201], v[104:107], v[64:79]
	ds_read_b128 v[198:201], v168 offset:13344
	v_lshl_add_u64 v[188:189], v[160:161], 0, s[10:11]
	v_lshlrev_b64 v[188:189], v148, v[188:189]
	s_waitcnt lgkmcnt(11)
	v_mfma_f32_32x32x16_bf16 v[64:79], v[202:205], v[108:111], v[64:79]
	ds_read_b128 v[202:205], v168 offset:17952
	v_lshl_add_u64 v[188:189], v[150:151], 0, v[188:189]
	global_load_dwordx4 v[124:127], v[188:189], off
	s_waitcnt lgkmcnt(11)
	v_mfma_f32_32x32x16_bf16 v[64:79], v[206:209], v[112:115], v[64:79]
	ds_read_b128 v[206:209], v168 offset:13376
	v_lshl_add_u64 v[188:189], v[158:159], 0, s[10:11]
	v_lshlrev_b64 v[188:189], v142, v[188:189]
	s_waitcnt lgkmcnt(11)
	v_mfma_f32_32x32x16_bf16 v[64:79], v[210:213], v[116:119], v[64:79]
	ds_read_b128 v[210:213], v168 offset:17984
	v_lshl_add_u64 v[188:189], v[152:153], 0, v[188:189]
	global_load_dwordx4 v[128:131], v[188:189], off
	s_waitcnt lgkmcnt(11)
	v_mfma_f32_32x32x16_bf16 v[80:95], v[214:217], v[96:99], v[16:31]
	ds_read_b128 v[214:217], v168 offset:13408
	global_load_dwordx4 v[132:135], v[156:157], off
	global_load_dwordx4 v[136:139], v[154:155], off
	s_waitcnt lgkmcnt(11)
	v_mfma_f32_32x32x16_bf16 v[80:95], v[218:221], v[100:103], v[80:95]
	ds_read_b128 v[218:221], v168 offset:18016
	s_waitcnt lgkmcnt(11)
	v_mfma_f32_32x32x16_bf16 v[80:95], v[222:225], v[104:107], v[80:95]
	s_waitcnt lgkmcnt(10)
	v_mfma_f32_32x32x16_bf16 v[80:95], v[226:229], v[108:111], v[80:95]
	s_waitcnt lgkmcnt(9)
	v_mfma_f32_32x32x16_bf16 v[80:95], v[230:233], v[112:115], v[80:95]
	s_waitcnt lgkmcnt(8)
	v_mfma_f32_32x32x16_bf16 v[80:95], v[234:237], v[116:119], v[80:95]
	s_setprio 0
.Lqk_join_C:
	v_max3_f32 v173, v64, v65, v66
	s_nop 9
	v_max3_f32 v174, v80, v81, v82
	v_max3_f32 v173, v173, v67, v68
	v_max3_f32 v174, v174, v83, v84
	v_max3_f32 v173, v173, v69, v70
	v_max3_f32 v174, v174, v85, v86
	v_max3_f32 v173, v173, v71, v72
	v_max3_f32 v174, v174, v87, v88
	v_max3_f32 v173, v173, v73, v74
	v_max3_f32 v174, v174, v89, v90
	v_max3_f32 v173, v173, v75, v76
	v_max3_f32 v174, v174, v91, v92
	v_max_f32_e32 v175, v95, v95
	v_max_f32_e32 v176, v79, v79
	v_max3_f32 v173, v173, v77, v78
	v_max3_f32 v174, v174, v93, v94
	v_max_f32_e32 v175, v176, v175
	v_max3_f32 v173, v173, v174, v175
	v_mov_b32_e32 v174, v173
	s_nop 1
	v_permlane32_swap_b32_e32 v173, v174
	v_max_f32_e32 v174, v174, v174
	v_max_f32_e32 v173, v173, v173
	v_max_f32_e32 v173, v173, v174
	v_cmp_lt_f32_e32 vcc, s45, v173
	s_cbranch_vccz .LBB0_440
	v_max_f32_e32 v173, v173, v173
	v_max_f32_e32 v173, 0, v173
	v_exp_f32_e64 v174, -v173
	v_sub_f32_e32 v31, v31, v173
	v_sub_f32_e32 v30, v30, v173
	v_sub_f32_e32 v29, v29, v173
	v_pk_mul_f32 v[62:63], v[62:63], v[174:175] op_sel_hi:[1,0]
	v_pk_mul_f32 v[60:61], v[60:61], v[174:175] op_sel_hi:[1,0]
	v_pk_mul_f32 v[58:59], v[58:59], v[174:175] op_sel_hi:[1,0]
	v_pk_mul_f32 v[56:57], v[56:57], v[174:175] op_sel_hi:[1,0]
	v_pk_mul_f32 v[54:55], v[54:55], v[174:175] op_sel_hi:[1,0]
	v_pk_mul_f32 v[52:53], v[52:53], v[174:175] op_sel_hi:[1,0]
	v_pk_mul_f32 v[50:51], v[50:51], v[174:175] op_sel_hi:[1,0]
	v_pk_mul_f32 v[48:49], v[48:49], v[174:175] op_sel_hi:[1,0]
	v_pk_mul_f32 v[46:47], v[46:47], v[174:175] op_sel_hi:[1,0]
	v_pk_mul_f32 v[44:45], v[44:45], v[174:175] op_sel_hi:[1,0]
	v_pk_mul_f32 v[42:43], v[42:43], v[174:175] op_sel_hi:[1,0]
	v_pk_mul_f32 v[40:41], v[40:41], v[174:175] op_sel_hi:[1,0]
	v_pk_mul_f32 v[38:39], v[38:39], v[174:175] op_sel_hi:[1,0]
	v_pk_mul_f32 v[36:37], v[36:37], v[174:175] op_sel_hi:[1,0]
	v_pk_mul_f32 v[34:35], v[34:35], v[174:175] op_sel_hi:[1,0]
	v_pk_mul_f32 v[32:33], v[32:33], v[174:175] op_sel_hi:[1,0]
	v_sub_f32_e32 v28, v28, v173
	v_sub_f32_e32 v27, v27, v173
	v_sub_f32_e32 v26, v26, v173
	v_sub_f32_e32 v25, v25, v173
	v_sub_f32_e32 v24, v24, v173
	v_sub_f32_e32 v23, v23, v173
	v_sub_f32_e32 v22, v22, v173
	v_sub_f32_e32 v21, v21, v173
	v_sub_f32_e32 v20, v20, v173
	v_sub_f32_e32 v19, v19, v173
	v_sub_f32_e32 v18, v18, v173
	v_sub_f32_e32 v17, v17, v173
	v_sub_f32_e32 v16, v16, v173
	v_sub_f32_e32 v64, v64, v173
	v_sub_f32_e32 v65, v65, v173
	v_sub_f32_e32 v66, v66, v173
	v_sub_f32_e32 v67, v67, v173
	v_sub_f32_e32 v68, v68, v173
	v_sub_f32_e32 v69, v69, v173
	v_sub_f32_e32 v70, v70, v173
	v_sub_f32_e32 v71, v71, v173
	v_sub_f32_e32 v72, v72, v173
	v_sub_f32_e32 v73, v73, v173
	v_sub_f32_e32 v74, v74, v173
	v_sub_f32_e32 v75, v75, v173
	v_sub_f32_e32 v76, v76, v173
	v_sub_f32_e32 v77, v77, v173
	v_sub_f32_e32 v78, v78, v173
	v_sub_f32_e32 v79, v79, v173
	v_sub_f32_e32 v80, v80, v173
	v_sub_f32_e32 v81, v81, v173
	v_sub_f32_e32 v82, v82, v173
	v_sub_f32_e32 v83, v83, v173
	v_sub_f32_e32 v84, v84, v173
	v_sub_f32_e32 v85, v85, v173
	v_sub_f32_e32 v86, v86, v173
	v_sub_f32_e32 v87, v87, v173
	v_sub_f32_e32 v88, v88, v173
	v_sub_f32_e32 v89, v89, v173
	v_sub_f32_e32 v90, v90, v173
	v_sub_f32_e32 v91, v91, v173
	v_sub_f32_e32 v92, v92, v173
	v_sub_f32_e32 v93, v93, v173
	v_sub_f32_e32 v94, v94, v173
	v_sub_f32_e32 v95, v95, v173
	v_pk_mul_f32 v[14:15], v[14:15], v[174:175] op_sel_hi:[1,0]
	v_pk_mul_f32 v[12:13], v[12:13], v[174:175] op_sel_hi:[1,0]
	v_pk_mul_f32 v[10:11], v[10:11], v[174:175] op_sel_hi:[1,0]
	v_pk_mul_f32 v[8:9], v[8:9], v[174:175] op_sel_hi:[1,0]
	v_pk_mul_f32 v[6:7], v[6:7], v[174:175] op_sel_hi:[1,0]
	v_pk_mul_f32 v[4:5], v[4:5], v[174:175] op_sel_hi:[1,0]
	v_pk_mul_f32 v[2:3], v[2:3], v[174:175] op_sel_hi:[1,0]
	v_pk_mul_f32 v[0:1], v[0:1], v[174:175] op_sel_hi:[1,0]

; #define MFMA32(a, b, c) __builtin_amdgcn_mfma_f32_32x32x16_bf16((a), (b), (c), 0, 0, 0)
; template <int DK, int DV>
; DI void attn_map(f32x16 (&O)[DV / 32], float& lsum, const u16* qrow, const u16* K1, int ldk1, const u16* K2, int ldk2, const u16* Vt, int nkeys, char* smem) {
;     ...
;     f32x16 s[2];
;     __builtin_amdgcn_s_setprio(1);
; #pragma unroll
;     for (int j = 0; j < 2; ++j) {
; #pragma unroll
;       for (int ks = 0; ks < DK / 16; ++ks) {
;         bf16x8 kf = *(const bf16x8*)(Ks + (j * 32 + r) * KST + ks * 16 + 8 * h);
;         s[j] = (ks == 0) ? MFMA32(kf, qf[ks], negm) : MFMA32(kf, qf[ks], s[j]);
;       }
;     }
;     {
;       constexpr int NQK = 2 * (DK / 16);
;       __builtin_amdgcn_sched_group_barrier(0x100, 2, 0);
; #pragma unroll
;       for (int q = 0; q < NQK - 2; ++q) { __builtin_amdgcn_sched_group_barrier(0x008, 1, 0); __builtin_amdgcn_sched_group_barrier(0x100, 1, 0); }
;       __builtin_amdgcn_sched_group_barrier(0x008, 2, 0);
;     }
;     __builtin_amdgcn_s_setprio(0);
.Lqk_last_C:
	s_setprio 1
	ds_read_b128 v[190:193], v143
	ds_read_b128 v[194:197], v143 offset:32
	ds_read_b128 v[198:201], v143 offset:64
	ds_read_b128 v[202:205], v143 offset:96
	ds_read_b128 v[206:209], v143 offset:128
	ds_read_b128 v[210:213], v143 offset:160
	ds_read_b128 v[214:217], v143 offset:6656
	ds_read_b128 v[218:221], v143 offset:6688
	ds_read_b128 v[222:225], v143 offset:6720
	ds_read_b128 v[226:229], v143 offset:6752
	ds_read_b128 v[230:233], v143 offset:6784
	ds_read_b128 v[234:237], v143 offset:6816
	s_waitcnt lgkmcnt(11)
	v_mfma_f32_32x32x16_bf16 v[64:79], v[190:193], v[96:99], v[16:31]
	ds_read_b128 v[190:193], v168 offset:13312
	s_waitcnt lgkmcnt(11)
	v_mfma_f32_32x32x16_bf16 v[64:79], v[194:197], v[100:103], v[64:79]
	ds_read_b128 v[194:197], v168 offset:17920
	s_waitcnt lgkmcnt(11)
	v_mfma_f32_32x32x16_bf16 v[64:79], v[198:201], v[104:107], v[64:79]
	ds_read_b128 v[198:201], v168 offset:13344
	s_waitcnt lgkmcnt(11)
	v_mfma_f32_32x32x16_bf16 v[64:79], v[202:205], v[108:111], v[64:79]
	ds_read_b128 v[202:205], v168 offset:17952
	s_waitcnt lgkmcnt(11)
	v_mfma_f32_32x32x16_bf16 v[64:79], v[206:209], v[112:115], v[64:79]
	ds_read_b128 v[206:209], v168 offset:13376
	s_waitcnt lgkmcnt(11)
	v_mfma_f32_32x32x16_bf16 v[64:79], v[210:213], v[116:119], v[64:79]
	ds_read_b128 v[210:213], v168 offset:17984
	s_waitcnt lgkmcnt(11)
	v_mfma_f32_32x32x16_bf16 v[80:95], v[214:217], v[96:99], v[16:31]
	ds_read_b128 v[214:217], v168 offset:13408
	s_waitcnt lgkmcnt(11)
	v_mfma_f32_32x32x16_bf16 v[80:95], v[218:221], v[100:103], v[80:95]
	ds_read_b128 v[218:221], v168 offset:18016
	s_waitcnt lgkmcnt(11)
	v_mfma_f32_32x32x16_bf16 v[80:95], v[222:225], v[104:107], v[80:95]
	s_waitcnt lgkmcnt(10)
	v_mfma_f32_32x32x16_bf16 v[80:95], v[226:229], v[108:111], v[80:95]
	s_waitcnt lgkmcnt(9)
	v_mfma_f32_32x32x16_bf16 v[80:95], v[230:233], v[112:115], v[80:95]
	s_waitcnt lgkmcnt(8)
	v_mfma_f32_32x32x16_bf16 v[80:95], v[234:237], v[116:119], v[80:95]
	s_setprio 0
	s_branch .Lqk_join_C

; #define MFMA32(a, b, c) __builtin_amdgcn_mfma_f32_32x32x16_bf16((a), (b), (c), 0, 0, 0)
; template <int DK, int DV>
; DI void attn_map(f32x16 (&O)[DV / 32], float& lsum, const u16* qrow, const u16* K1, int ldk1, const u16* K2, int ldk2, const u16* Vt, int nkeys, char* smem) {
;     ...
;   for (int k0 = 0; k0 < nkeys; k0 += 64) {
;     __syncthreads();
; #pragma unroll
;     for (int i = 0; i < NKR; ++i) { int id = tid + i * 256; int row = id / KCH, cc = id - row * KCH; *(u32x4*)(Ks + row * KST + cc * 8) = kreg[i]; }
; #pragma unroll
;     for (int i = 0; i < NVR; ++i) {
;       int id = tid + i * 256; int row = id >> 3, cc = id & 7;
;       u16* base = Vs + row * VST + (cc >> 1) * 16 + (cc & 1) * 4;
;       u32x2 t0 = {vreg[i].x, vreg[i].y}, t1 = {vreg[i].z, vreg[i].w};
;       *(u32x2*)base = t0; *(u32x2*)(base + 8) = t1;
;     }
;     __syncthreads();
;     if (k0 + 64 < nkeys) ATT_LOAD(k0 + 64)
;     f32x16 s[2];
;     __builtin_amdgcn_s_setprio(1);
; #pragma unroll
;     for (int j = 0; j < 2; ++j) {
; #pragma unroll
;       for (int ks = 0; ks < DK / 16; ++ks) {
;         bf16x8 kf = *(const bf16x8*)(Ks + (j * 32 + r) * KST + ks * 16 + 8 * h);
;         s[j] = (ks == 0) ? MFMA32(kf, qf[ks], negm) : MFMA32(kf, qf[ks], s[j]);
;       }
;     }
;     {
;       constexpr int NQK = 2 * (DK / 16);
;       __builtin_amdgcn_sched_group_barrier(0x100, 2, 0);
; #pragma unroll
;       for (int q = 0; q < NQK - 2; ++q) { __builtin_amdgcn_sched_group_barrier(0x008, 1, 0); __builtin_amdgcn_sched_group_barrier(0x100, 1, 0); }
;       __builtin_amdgcn_sched_group_barrier(0x008, 2, 0);
;     }
;     __builtin_amdgcn_s_setprio(0);
.LBB0_447:
	s_cmpk_gt_u32 s12, 0x10bf
	s_cselect_b64 s[8:9], -1, 0
	s_and_b64 vcc, exec, s[8:9]
	s_barrier
	s_waitcnt vmcnt(3)
	ds_write_b128 v139, v[112:115]
	s_waitcnt vmcnt(1)
	ds_write_b128 v140, v[116:119]
	ds_write2_b64 v141, v[120:121], v[122:123] offset0:128 offset1:130
	s_waitcnt vmcnt(0)
	ds_write2_b64 v142, v[124:125], v[126:127] offset0:128 offset1:130
	s_waitcnt lgkmcnt(0)
	s_barrier
	s_cbranch_vccnz .Lqk_last_D
	s_setprio 1
	ds_read_b128 v[200:203], v143
	ds_read_b128 v[204:207], v143 offset:32
	ds_read_b128 v[208:211], v143 offset:64
	ds_read_b128 v[212:215], v143 offset:96
	ds_read_b128 v[216:219], v143 offset:4608
	ds_read_b128 v[220:223], v143 offset:4640
	ds_read_b128 v[224:227], v143 offset:4672
	ds_read_b128 v[228:231], v143 offset:4704
	s_waitcnt lgkmcnt(7)
	v_mfma_f32_32x32x16_bf16 v[64:79], v[200:203], v[96:99], v[16:31]
	ds_read_b128 v[200:203], v143 offset:9216
	v_lshl_add_u64 v[236:237], v[136:137], 0, s[6:7]
	global_load_dwordx4 v[112:115], v[236:237], off
	s_waitcnt lgkmcnt(7)
	v_mfma_f32_32x32x16_bf16 v[64:79], v[204:207], v[100:103], v[64:79]
	ds_read_b128 v[204:207], v143 offset:13824
	v_lshl_add_u64 v[236:237], v[134:135], 0, s[6:7]
	global_load_dwordx4 v[116:119], v[236:237], off
	s_waitcnt lgkmcnt(7)
	v_mfma_f32_32x32x16_bf16 v[64:79], v[208:211], v[104:107], v[64:79]
	ds_read_b128 v[208:211], v143 offset:9248
	v_lshl_add_u64 v[236:237], v[132:133], 0, s[6:7]
	global_load_dwordx4 v[120:123], v[236:237], off
	s_waitcnt lgkmcnt(7)
	v_mfma_f32_32x32x16_bf16 v[64:79], v[212:215], v[108:111], v[64:79]
	ds_read_b128 v[212:215], v143 offset:13856
	v_lshl_add_u64 v[236:237], v[130:131], 0, s[6:7]
	global_load_dwordx4 v[124:127], v[236:237], off
	s_waitcnt lgkmcnt(7)
	v_mfma_f32_32x32x16_bf16 v[80:95], v[216:219], v[96:99], v[16:31]
	ds_read_b128 v[216:219], v143 offset:9280
	s_waitcnt lgkmcnt(7)
	v_mfma_f32_32x32x16_bf16 v[80:95], v[220:223], v[100:103], v[80:95]
	ds_read_b128 v[220:223], v143 offset:13888
	s_waitcnt lgkmcnt(7)
	v_mfma_f32_32x32x16_bf16 v[80:95], v[224:227], v[104:107], v[80:95]
	ds_read_b128 v[224:227], v143 offset:9312
	s_waitcnt lgkmcnt(7)
	v_mfma_f32_32x32x16_bf16 v[80:95], v[228:231], v[108:111], v[80:95]
	ds_read_b128 v[228:231], v143 offset:13920
	s_setprio 0
; #define MFMA32(a, b, c) __builtin_amdgcn_mfma_f32_32x32x16_bf16((a), (b), (c), 0, 0, 0)
; DI float xmax32(float x) { auto t = __builtin_amdgcn_permlane32_swap(__float_as_uint(x), __float_as_uint(x), false, false); return fmaxf(__uint_as_float(t[0]), __uint_as_float(t[1])); }
; template <int DK, int DV>
; DI void attn_map(f32x16 (&O)[DV / 32], float& lsum, const u16* qrow, const u16* K1, int ldk1, const u16* K2, int ldk2, const u16* Vt, int nkeys, char* smem) {
;     ...
;     f32x16 s[2];
;     __builtin_amdgcn_s_setprio(1);
; #pragma unroll
;     for (int j = 0; j < 2; ++j) {
; #pragma unroll
;       for (int ks = 0; ks < DK / 16; ++ks) {
;         bf16x8 kf = *(const bf16x8*)(Ks + (j * 32 + r) * KST + ks * 16 + 8 * h);
;         s[j] = (ks == 0) ? MFMA32(kf, qf[ks], negm) : MFMA32(kf, qf[ks], s[j]);
;       }
;     }
;     {
;       constexpr int NQK = 2 * (DK / 16);
;       __builtin_amdgcn_sched_group_barrier(0x100, 2, 0);
; #pragma unroll
;       for (int q = 0; q < NQK - 2; ++q) { __builtin_amdgcn_sched_group_barrier(0x008, 1, 0); __builtin_amdgcn_sched_group_barrier(0x100, 1, 0); }
;       __builtin_amdgcn_sched_group_barrier(0x008, 2, 0);
;     }
;     ...
;     float mx0 = fmaxf(fmaxf(s[0][0], s[0][1]), s[0][2]), mx1 = fmaxf(fmaxf(s[1][0], s[1][1]), s[1][2]);
; #pragma unroll
;     for (int i = 3; i < 15; i += 2) { mx0 = fmaxf(fmaxf(mx0, s[0][i]), s[0][i + 1]); mx1 = fmaxf(fmaxf(mx1, s[1][i]), s[1][i + 1]); }
;     float mx = fmaxf(fmaxf(mx0, mx1), fmaxf(s[0][15], s[1][15]));
;     mx = xmax32(mx);
;     const bool first = (k0 == 0);
;     if (first || __any(mx > 6.f)) {
;       float dl = first ? mx : fmaxf(mx, 0.f);
;       float alpha = __builtin_amdgcn_exp2f(-dl);
; #pragma unroll
;       for (int i = 0; i < 16; ++i) { negm[i] -= dl; lacc[i] *= alpha; }
; #pragma unroll
;       for (int dd = 0; dd < DV / 32; ++dd)
; #pragma unroll
;         for (int i = 0; i < 16; ++i) O[dd][i] *= alpha;
; #pragma unroll
;       for (int j = 0; j < 2; ++j)
; #pragma unroll
;         for (int i = 0; i < 16; ++i) s[j][i] -= dl;
;     }
.Lqk_join_D:
	s_nop 0
	v_max3_f32 v144, v64, v65, v66
	s_nop 8
	v_max3_f32 v145, v80, v81, v82
	v_max3_f32 v144, v144, v67, v68
	v_max3_f32 v145, v145, v83, v84
	v_max3_f32 v144, v144, v69, v70
	v_max3_f32 v145, v145, v85, v86
	v_max3_f32 v144, v144, v71, v72
	v_max3_f32 v145, v145, v87, v88
	v_max3_f32 v144, v144, v73, v74
	v_max3_f32 v145, v145, v89, v90
	v_max3_f32 v144, v144, v75, v76
	v_max3_f32 v145, v145, v91, v92
	v_max_f32_e32 v146, v95, v95
	v_max_f32_e32 v147, v79, v79
	v_max3_f32 v144, v144, v77, v78
	v_max3_f32 v145, v145, v93, v94
	v_max_f32_e32 v146, v147, v146
	v_max3_f32 v144, v144, v145, v146
	v_mov_b32_e32 v145, v144
	s_nop 1
	v_permlane32_swap_b32_e32 v144, v145
	v_max_f32_e32 v145, v145, v145
	v_max_f32_e32 v144, v144, v144
	v_max_f32_e32 v144, v144, v145
	v_cmp_lt_f32_e32 vcc, s45, v144
	s_cbranch_vccz .LBB0_446
	v_max_f32_e32 v144, v144, v144
	v_max_f32_e32 v145, 0, v144
	v_exp_f32_e64 v144, -v145
	v_sub_f32_e32 v31, v31, v145
	v_sub_f32_e32 v30, v30, v145
	v_sub_f32_e32 v29, v29, v145
	v_pk_mul_f32 v[62:63], v[62:63], v[144:145] op_sel_hi:[1,0]
	v_pk_mul_f32 v[60:61], v[60:61], v[144:145] op_sel_hi:[1,0]
	v_pk_mul_f32 v[58:59], v[58:59], v[144:145] op_sel_hi:[1,0]
	v_pk_mul_f32 v[56:57], v[56:57], v[144:145] op_sel_hi:[1,0]
	v_pk_mul_f32 v[54:55], v[54:55], v[144:145] op_sel_hi:[1,0]
	v_pk_mul_f32 v[52:53], v[52:53], v[144:145] op_sel_hi:[1,0]
	v_pk_mul_f32 v[50:51], v[50:51], v[144:145] op_sel_hi:[1,0]
	v_pk_mul_f32 v[48:49], v[48:49], v[144:145] op_sel_hi:[1,0]
	v_pk_mul_f32 v[46:47], v[46:47], v[144:145] op_sel_hi:[1,0]
	v_pk_mul_f32 v[44:45], v[44:45], v[144:145] op_sel_hi:[1,0]
	v_pk_mul_f32 v[42:43], v[42:43], v[144:145] op_sel_hi:[1,0]
	v_pk_mul_f32 v[40:41], v[40:41], v[144:145] op_sel_hi:[1,0]
	v_pk_mul_f32 v[38:39], v[38:39], v[144:145] op_sel_hi:[1,0]
	v_pk_mul_f32 v[36:37], v[36:37], v[144:145] op_sel_hi:[1,0]
	v_pk_mul_f32 v[34:35], v[34:35], v[144:145] op_sel_hi:[1,0]
	v_pk_mul_f32 v[32:33], v[32:33], v[144:145] op_sel_hi:[1,0]
	v_sub_f32_e32 v28, v28, v145
	v_sub_f32_e32 v27, v27, v145
	v_sub_f32_e32 v26, v26, v145
	v_sub_f32_e32 v25, v25, v145
	v_sub_f32_e32 v24, v24, v145
	v_sub_f32_e32 v23, v23, v145
	v_sub_f32_e32 v22, v22, v145
	v_sub_f32_e32 v21, v21, v145
	v_sub_f32_e32 v20, v20, v145
	v_sub_f32_e32 v19, v19, v145
	v_sub_f32_e32 v18, v18, v145
	v_sub_f32_e32 v17, v17, v145
	v_sub_f32_e32 v16, v16, v145
	v_sub_f32_e32 v64, v64, v145
	v_sub_f32_e32 v65, v65, v145
	v_sub_f32_e32 v66, v66, v145
	v_sub_f32_e32 v67, v67, v145
	v_sub_f32_e32 v68, v68, v145
	v_sub_f32_e32 v69, v69, v145
	v_sub_f32_e32 v70, v70, v145
	v_sub_f32_e32 v71, v71, v145
	v_sub_f32_e32 v72, v72, v145
	v_sub_f32_e32 v73, v73, v145
	v_sub_f32_e32 v74, v74, v145
	v_sub_f32_e32 v75, v75, v145
	v_sub_f32_e32 v76, v76, v145
	v_sub_f32_e32 v77, v77, v145
	v_sub_f32_e32 v78, v78, v145
	v_sub_f32_e32 v79, v79, v145
	v_sub_f32_e32 v80, v80, v145
	v_sub_f32_e32 v81, v81, v145
	v_sub_f32_e32 v82, v82, v145
	v_sub_f32_e32 v83, v83, v145
	v_sub_f32_e32 v84, v84, v145
	v_sub_f32_e32 v85, v85, v145
	v_sub_f32_e32 v86, v86, v145
	v_sub_f32_e32 v87, v87, v145
	v_sub_f32_e32 v88, v88, v145
	v_sub_f32_e32 v89, v89, v145
	v_sub_f32_e32 v90, v90, v145
	v_sub_f32_e32 v91, v91, v145
	v_sub_f32_e32 v92, v92, v145
	v_sub_f32_e32 v93, v93, v145
	v_sub_f32_e32 v94, v94, v145
	v_sub_f32_e32 v95, v95, v145
	v_pk_mul_f32 v[14:15], v[14:15], v[144:145] op_sel_hi:[1,0]
	v_pk_mul_f32 v[12:13], v[12:13], v[144:145] op_sel_hi:[1,0]
	v_pk_mul_f32 v[10:11], v[10:11], v[144:145] op_sel_hi:[1,0]
	v_pk_mul_f32 v[8:9], v[8:9], v[144:145] op_sel_hi:[1,0]
	v_pk_mul_f32 v[6:7], v[6:7], v[144:145] op_sel_hi:[1,0]
	v_pk_mul_f32 v[4:5], v[4:5], v[144:145] op_sel_hi:[1,0]
	v_pk_mul_f32 v[2:3], v[2:3], v[144:145] op_sel_hi:[1,0]
	v_pk_mul_f32 v[0:1], v[0:1], v[144:145] op_sel_hi:[1,0]
	s_branch .LBB0_446
.Lqk_last_D:
	s_setprio 1
	ds_read_b128 v[200:203], v143
	ds_read_b128 v[204:207], v143 offset:32
	ds_read_b128 v[208:211], v143 offset:64
	ds_read_b128 v[212:215], v143 offset:96
	ds_read_b128 v[216:219], v143 offset:4608
	ds_read_b128 v[220:223], v143 offset:4640
	ds_read_b128 v[224:227], v143 offset:4672
	ds_read_b128 v[228:231], v143 offset:4704
	s_waitcnt lgkmcnt(7)
	v_mfma_f32_32x32x16_bf16 v[64:79], v[200:203], v[96:99], v[16:31]
	ds_read_b128 v[200:203], v143 offset:9216
	s_waitcnt lgkmcnt(7)
	v_mfma_f32_32x32x16_bf16 v[64:79], v[204:207], v[100:103], v[64:79]
	ds_read_b128 v[204:207], v143 offset:13824
	s_waitcnt lgkmcnt(7)
	v_mfma_f32_32x32x16_bf16 v[64:79], v[208:211], v[104:107], v[64:79]
	ds_read_b128 v[208:211], v143 offset:9248
	s_waitcnt lgkmcnt(7)
	v_mfma_f32_32x32x16_bf16 v[64:79], v[212:215], v[108:111], v[64:79]
	ds_read_b128 v[212:215], v143 offset:13856
	s_waitcnt lgkmcnt(7)
	v_mfma_f32_32x32x16_bf16 v[80:95], v[216:219], v[96:99], v[16:31]
	ds_read_b128 v[216:219], v143 offset:9280
	s_waitcnt lgkmcnt(7)
	v_mfma_f32_32x32x16_bf16 v[80:95], v[220:223], v[100:103], v[80:95]
	ds_read_b128 v[220:223], v143 offset:13888
	s_waitcnt lgkmcnt(7)
	v_mfma_f32_32x32x16_bf16 v[80:95], v[224:227], v[104:107], v[80:95]
	ds_read_b128 v[224:227], v143 offset:9312
	s_waitcnt lgkmcnt(7)
	v_mfma_f32_32x32x16_bf16 v[80:95], v[228:231], v[108:111], v[80:95]
	ds_read_b128 v[228:231], v143 offset:13920
	s_setprio 0
	s_branch .Lqk_join_D

; DI int vblock() { int nb = gridDim.x, b = blockIdx.x; return ((nb & 7) == 0) ? (b & 7) * (nb >> 3) + (b >> 3) : b; }
; template <int BN>
; DI void gemm_main(f32x16 (&acc)[2][BN / 64], const GDesc& cur, const GDesc& nxt, GRegs<BN>& R, bool preloaded, char* smem) {
;     ...
;   const u16* ap = cur.A + (size_t)(cur.m0 + (tid >> 3)) * cur.lda + (tid & 7) * 8;
;   const u16* wp = cur.W + (size_t)(cur.n0 + (tid >> 3)) * cur.ldw + (tid & 7) * 8;
;   const u16* apn = nxt.A + (size_t)(nxt.m0 + (tid >> 3)) * nxt.lda + (tid & 7) * 8;
;   const u16* wpn = nxt.W + (size_t)(nxt.n0 + (tid >> 3)) * nxt.ldw + (tid & 7) * 8;
;   const int lda = cur.lda, ldw = cur.ldw, K = cur.K;
;   u16* asw = As + (tid >> 3) * 72 + (tid & 7) * 8;
;   u16* bsw = Bs + (tid >> 3) * 72 + (tid & 7) * 8;
;     ...
;   if (!preloaded) {
;     GM_LOAD(R.ra0, R.rb0, ap, wp, lda, ldw, 0)
;     GM_LOAD(R.ra1, R.rb1, ap, wp, lda, ldw, 64)
;   }
; DI void phase_mla_up(const Params& P, int layer, char* smem) {
;     ...
;   for (int job = vblock(); job < MT_TILES * 14; job += gridDim.x) {
;     int mt, nt; tile_map(job, 14, mt, nt);
;     bool isq = nt < 6;
;     int m0 = mt * 128, n0 = (isq ? nt : nt - 6) * 128;
;     int b = m0 / TB, pos0 = m0 - b * TB;
;     const u16* A = (const u16*)(P.ws + (isq ? OFF_CQ : OFF_CKV));
;     int K = isq ? 384 : 256;
;     const u16* W = (const u16*)(P.ws + (size_t)layer * SZ_WLAYER + (isq ? OFF_WUQ : OFF_WUKV));
;     const float* rs = (const float*)(P.ws + (isq ? OFF_RSQ : OFF_RSKV)) + m0;
;     f32x16 acc[2][2];
;     zero_acc<2>(acc);
;     { GRegs<128> R; const GDesc dc = gdesc(A, K, W, K, K, m0, n0); GDesc dn = dc; dn.valid = 0; gemm_main<128>(acc, dc, dn, R, false, smem); }
.LBB0_535:
	s_and_b32 s4, s30, 7
	s_lshl_b32 s34, s4, 7
	s_mul_hi_i32 s4, s31, 0x92492493
	s_add_i32 s4, s4, s31
	s_lshr_b32 s6, s4, 31
	s_ashr_i32 s4, s4, 6
	s_add_i32 s35, s4, s6
	s_mul_i32 s4, s35, 0xffffff90
	s_add_i32 s4, s4, s31
	s_lshl_b32 s6, s35, 3
	s_and_b32 s7, s31, 7
	s_or_b32 s17, s6, s7
	s_ashr_i32 s4, s4, 3
	s_cmp_lt_i32 s4, 6
	s_cselect_b64 s[12:13], -1, 0
	s_cmp_gt_i32 s4, 5
	s_cselect_b64 s[26:27], -1, 0
	s_lshl_b32 s4, s4, 7
	s_lshl_b32 s16, s17, 7
	s_add_i32 s7, s4, 0xfffffd00
	s_and_b64 s[14:15], s[12:13], exec
	s_cselect_b32 s6, s4, s7
	s_mov_b32 s4, 0x1d090100
	s_cselect_b32 s4, 0x1b710100, s4
	s_add_u32 s14, s76, s4
	s_addc_u32 s15, s77, 0
	s_and_b64 s[24:25], s[12:13], exec
	s_movk_i32 s4, 0x180
	v_mov_b32_e32 v22, v171
	s_cselect_b32 s22, s4, 0x100
	s_mov_b32 s4, 0x1800000
	s_cselect_b32 s4, s4, 0x1890000
	v_ashrrev_i32_e32 v23, 3, v22
	v_readlane_b32 s24, v254, 31
	v_add_u32_e32 v0, s16, v23
	v_lshlrev_b32_e32 v4, 4, v22
	v_readlane_b32 s25, v254, 32
	s_add_u32 s24, s24, s4
	v_mad_i64_i32 v[0:1], s[28:29], s22, v0, 0
	v_and_b32_e32 v168, 0x70, v4
	v_add_u32_e32 v4, s6, v23
	s_addc_u32 s25, s25, 0
	v_mov_b64_e32 v[2:3], s[14:15]
	v_lshl_add_u64 v[0:1], v[0:1], 1, s[14:15]
	v_mad_i64_i32 v[6:7], s[14:15], v4, s22, 0
	v_lshl_add_u64 v[134:135], v[6:7], 1, s[24:25]
	v_lshl_add_u64 v[0:1], v[0:1], 0, v[168:169]
	s_lshl_b32 s4, s22, 6
	v_lshl_add_u64 v[14:15], v[134:135], 0, v[168:169]
	v_lshl_add_u64 v[6:7], v[0:1], 0, s[4:5]
	v_lshl_add_u64 v[16:17], v[14:15], 0, s[4:5]
	v_lshl_add_u64 v[10:11], v[6:7], 0, s[4:5]
	v_lshl_add_u64 v[18:19], v[16:17], 0, s[4:5]
	v_lshl_add_u64 v[12:13], v[10:11], 0, s[4:5]
	v_lshl_add_u64 v[20:21], v[18:19], 0, s[4:5]
	global_load_dwordx4 v[64:67], v[0:1], off
	global_load_dwordx4 v[72:75], v[6:7], off
	global_load_dwordx4 v[80:83], v[10:11], off
	global_load_dwordx4 v[88:91], v[12:13], off
	global_load_dwordx4 v[96:99], v[14:15], off
	global_load_dwordx4 v[104:107], v[16:17], off
	global_load_dwordx4 v[112:115], v[18:19], off
	global_load_dwordx4 v[120:123], v[20:21], off
	global_load_dwordx4 v[68:71], v[0:1], off offset:128
	global_load_dwordx4 v[76:79], v[6:7], off offset:128
	global_load_dwordx4 v[84:87], v[10:11], off offset:128
	global_load_dwordx4 v[92:95], v[12:13], off offset:128
	global_load_dwordx4 v[100:103], v[14:15], off offset:128
	global_load_dwordx4 v[108:111], v[16:17], off offset:128
	global_load_dwordx4 v[116:119], v[18:19], off offset:128
	global_load_dwordx4 v[124:127], v[20:21], off offset:128
	v_and_b32_e32 v0, 31, v22
	v_lshrrev_b32_e32 v1, 1, v22
	v_and_or_b32 v0, v1, s54, v0
	v_ashrrev_i32_e32 v5, 31, v4
	v_and_b32_e32 v10, 16, v1
	v_and_b32_e32 v1, 0x5f, v22
	v_mul_lo_u32 v11, v0, s53
	v_and_b32_e32 v0, 7, v22
	v_mad_u64_u32 v[136:137], s[14:15], v23, s53, v[168:169]
	v_mul_u32_u24_e32 v12, 0x90, v1
	v_lshlrev_b32_e32 v168, 4, v0
	v_lshlrev_b64 v[0:1], 1, v[4:5]
	v_mov_b64_e32 v[8:9], s[24:25]
	v_lshl_add_u64 v[4:5], v[0:1], 0, s[56:57]
	v_mad_u64_u32 v[138:139], s[14:15], v4, s22, v[8:9]
	s_mov_b64 s[24:25], 0xc0
	v_mad_i32_i24 v139, v5, s22, v139
	v_lshl_add_u64 v[4:5], v[0:1], 0, s[24:25]
	v_lshl_add_u64 v[0:1], v[0:1], 0, 64
	v_mad_u64_u32 v[140:141], s[14:15], v4, s22, v[8:9]
	v_mad_u64_u32 v[142:143], s[14:15], v0, s22, v[8:9]
	s_lshl_b32 s14, s35, 10
	s_or_b32 s14, s34, s14
	v_add_u32_e32 v0, s14, v23
	v_mad_i32_i24 v143, v1, s22, v143
	v_ashrrev_i32_e32 v1, 31, v0
	v_mad_i32_i24 v141, v5, s22, v141
	v_lshlrev_b64 v[4:5], 1, v[0:1]
	v_lshl_add_u64 v[6:7], v[4:5], 0, s[56:57]
	v_mad_u64_u32 v[144:145], s[14:15], v6, s22, v[2:3]
	v_mad_i32_i24 v145, v7, s22, v145
	v_lshl_add_u64 v[6:7], v[4:5], 0, s[24:25]
	v_mad_u64_u32 v[146:147], s[14:15], v6, s22, v[2:3]
	v_mad_i32_i24 v147, v7, s22, v147
	v_lshl_add_u64 v[6:7], v[4:5], 0, 64
	v_alignbit_b32 v0, v1, v0, 31
	v_mad_u64_u32 v[150:151], s[14:15], v4, s22, v[2:3]
	v_mad_u64_u32 v[148:149], s[14:15], v6, s22, v[2:3]
	v_mad_i32_i24 v151, v0, s22, v151
	v_mov_b32_e32 v0, 0
	s_mov_b32 s23, 0
	s_add_i32 s4, s22, 0xffffff40
	v_mad_i32_i24 v149, v7, s22, v149
	v_add_u32_e32 v137, v10, v11
	v_add_u32_e32 v185, v10, v12
	v_mov_b32_e32 v1, v0
	v_mov_b32_e32 v2, v0
	v_mov_b32_e32 v3, v0
	v_mov_b32_e32 v4, v0
	v_mov_b32_e32 v5, v0
	v_mov_b32_e32 v6, v0
	v_mov_b32_e32 v7, v0
	v_mov_b32_e32 v8, v0
	v_mov_b32_e32 v9, v0
	v_mov_b32_e32 v10, v0
	v_mov_b32_e32 v11, v0
	v_mov_b32_e32 v12, v0
	v_mov_b32_e32 v13, v0
	v_mov_b32_e32 v14, v0
	v_mov_b32_e32 v15, v0
	v_mov_b32_e32 v32, v0
	v_mov_b32_e32 v33, v0
	v_mov_b32_e32 v34, v0
	v_mov_b32_e32 v35, v0
	v_mov_b32_e32 v36, v0
	v_mov_b32_e32 v37, v0
	v_mov_b32_e32 v38, v0
	v_mov_b32_e32 v39, v0
	v_mov_b32_e32 v40, v0
	v_mov_b32_e32 v41, v0
	v_mov_b32_e32 v42, v0
	v_mov_b32_e32 v43, v0
	v_mov_b32_e32 v44, v0
	v_mov_b32_e32 v45, v0
	v_mov_b32_e32 v46, v0
	v_mov_b32_e32 v47, v0
	v_mov_b32_e32 v16, v0
	v_mov_b32_e32 v17, v0
	v_mov_b32_e32 v18, v0
	v_mov_b32_e32 v19, v0
	v_mov_b32_e32 v20, v0
	v_mov_b32_e32 v21, v0
	v_mov_b32_e32 v22, v0
	v_mov_b32_e32 v23, v0
	v_mov_b32_e32 v24, v0
	v_mov_b32_e32 v25, v0
	v_mov_b32_e32 v26, v0
	v_mov_b32_e32 v27, v0
	v_mov_b32_e32 v28, v0
	v_mov_b32_e32 v29, v0
	v_mov_b32_e32 v30, v0
	v_mov_b32_e32 v31, v0
	v_mov_b32_e32 v48, v0
	v_mov_b32_e32 v49, v0
	v_mov_b32_e32 v50, v0
	v_mov_b32_e32 v51, v0
	v_mov_b32_e32 v52, v0
	v_mov_b32_e32 v53, v0
	v_mov_b32_e32 v54, v0
	v_mov_b32_e32 v55, v0
	v_mov_b32_e32 v56, v0
	v_mov_b32_e32 v57, v0
	v_mov_b32_e32 v58, v0
	v_mov_b32_e32 v59, v0
	v_mov_b32_e32 v60, v0
	v_mov_b32_e32 v61, v0
	v_mov_b32_e32 v62, v0
	v_mov_b32_e32 v63, v0
	s_branch .LBB0_537

; template <int BN>
; DI void gemm_main(f32x16 (&acc)[2][BN / 64], const GDesc& cur, const GDesc& nxt, GRegs<BN>& R, bool preloaded, char* smem) {
;     ...
;   for (int k0 = 0; k0 < K; k0 += 128) {
;     __syncthreads();
;     GM_STORE(R.ra0, R.rb0)
;     __syncthreads();
;     if (k0 + 128 < K) GM_LOAD(R.ra0, R.rb0, ap, wp, lda, ldw, k0 + 128)
;     else if (nxt.valid) GM_LOAD(R.ra0, R.rb0, apn, wpn, nxt.lda, nxt.ldw, 0)
;     GM_COMPUTE()
;     __syncthreads();
;     GM_STORE(R.ra1, R.rb1)
;     __syncthreads();
;     if (k0 + 192 < K) GM_LOAD(R.ra1, R.rb1, ap, wp, lda, ldw, k0 + 192)
;     else if (nxt.valid) GM_LOAD(R.ra1, R.rb1, apn, wpn, nxt.lda, nxt.ldw, 64)
;     GM_COMPUTE()
.Lt1_g3:
	v_lshl_add_u64 v[138:139], v[138:139], 0, s[88:89]
	v_lshl_add_u64 v[140:141], v[140:141], 0, s[88:89]
	v_lshl_add_u64 v[142:143], v[142:143], 0, s[88:89]
	v_lshl_add_u64 v[134:135], v[134:135], 0, s[88:89]
	v_lshl_add_u64 v[144:145], v[144:145], 0, s[88:89]
	v_lshl_add_u64 v[146:147], v[146:147], 0, s[88:89]
	v_lshl_add_u64 v[148:149], v[148:149], 0, s[88:89]
	v_lshl_add_u64 v[150:151], v[150:151], 0, s[88:89]
	s_andn2_b64 vcc, exec, s[14:15]
	s_mov_b32 s23, s24
	s_cbranch_vccz .LBB0_541
.LBB0_537:
	s_add_i32 s24, s23, 0x80
	s_cmp_ge_u32 s24, s22
	s_cselect_b64 s[14:15], -1, 0
	s_and_b64 vcc, exec, s[14:15]
	v_lshl_add_u64 v[152:153], v[150:151], 0, v[168:169]
	v_lshl_add_u64 v[154:155], v[148:149], 0, v[168:169]
	v_lshl_add_u64 v[156:157], v[144:145], 0, v[168:169]
	v_lshl_add_u64 v[158:159], v[146:147], 0, v[168:169]
	v_lshl_add_u64 v[160:161], v[134:135], 0, v[168:169]
	v_lshl_add_u64 v[162:163], v[142:143], 0, v[168:169]
	v_lshl_add_u64 v[164:165], v[138:139], 0, v[168:169]
	v_lshl_add_u64 v[166:167], v[140:141], 0, v[168:169]
	s_barrier
	s_waitcnt vmcnt(15)
	ds_write_b128 v136, v[64:67]
	s_waitcnt vmcnt(14)
	ds_write_b128 v136, v[72:75] offset:4608
	s_waitcnt vmcnt(13)
	ds_write_b128 v136, v[80:83] offset:9216
	s_waitcnt vmcnt(12)
	ds_write_b128 v136, v[88:91] offset:13824
	s_waitcnt vmcnt(11)
	ds_write_b128 v136, v[96:99] offset:18432
	s_waitcnt vmcnt(10)
	ds_write_b128 v136, v[104:107] offset:23040
	s_waitcnt vmcnt(9)
	ds_write_b128 v136, v[112:115] offset:27648
	s_waitcnt vmcnt(8)
	ds_write_b128 v136, v[120:123] offset:32256
	s_waitcnt lgkmcnt(0)
	s_barrier
	s_cbranch_vccnz .Lnopf_g3
	s_setprio 1
	ds_read_b128 v[186:189], v137
	ds_read_b128 v[190:193], v185 offset:23040
	ds_read_b128 v[194:197], v137 offset:4608
	ds_read_b128 v[198:201], v137 offset:32
	s_waitcnt lgkmcnt(2)
	v_mfma_f32_32x32x16_bf16 v[16:31], v[186:189], v[190:193], v[16:31]
	ds_read_b128 v[202:205], v185 offset:18432
	s_waitcnt lgkmcnt(0)
	v_mfma_f32_32x32x16_bf16 v[48:63], v[186:189], v[202:205], v[48:63]
	ds_read_b128 v[186:189], v185 offset:18464
	v_mfma_f32_32x32x16_bf16 v[32:47], v[194:197], v[202:205], v[32:47]
	ds_read_b128 v[202:205], v137 offset:4640
	global_load_dwordx4 v[64:67], v[152:153], off offset:256
	v_mfma_f32_32x32x16_bf16 v[0:15], v[194:197], v[190:193], v[0:15]
	ds_read_b128 v[190:193], v185 offset:23072
	global_load_dwordx4 v[72:75], v[154:155], off offset:256
	s_waitcnt lgkmcnt(2)
	v_mfma_f32_32x32x16_bf16 v[48:63], v[198:201], v[186:189], v[48:63]
	ds_read_b128 v[194:197], v137 offset:64
	global_load_dwordx4 v[80:83], v[156:157], off offset:256
	s_waitcnt lgkmcnt(1)
	v_mfma_f32_32x32x16_bf16 v[16:31], v[198:201], v[190:193], v[16:31]
	ds_read_b128 v[198:201], v137 offset:4672
	global_load_dwordx4 v[88:91], v[158:159], off offset:256
	v_mfma_f32_32x32x16_bf16 v[32:47], v[202:205], v[186:189], v[32:47]
	ds_read_b128 v[186:189], v185 offset:18496
	global_load_dwordx4 v[96:99], v[160:161], off offset:256
	v_mfma_f32_32x32x16_bf16 v[0:15], v[202:205], v[190:193], v[0:15]
	ds_read_b128 v[190:193], v185 offset:23104
	global_load_dwordx4 v[104:107], v[162:163], off offset:256
	s_waitcnt lgkmcnt(1)
	v_mfma_f32_32x32x16_bf16 v[48:63], v[194:197], v[186:189], v[48:63]
	ds_read_b128 v[202:205], v137 offset:96
	global_load_dwordx4 v[112:115], v[164:165], off offset:256
	s_waitcnt lgkmcnt(1)
	v_mfma_f32_32x32x16_bf16 v[16:31], v[194:197], v[190:193], v[16:31]
	ds_read_b128 v[194:197], v137 offset:4704
	global_load_dwordx4 v[120:123], v[166:167], off offset:256
	v_mfma_f32_32x32x16_bf16 v[32:47], v[198:201], v[186:189], v[32:47]
	ds_read_b128 v[186:189], v185 offset:18528
	v_mfma_f32_32x32x16_bf16 v[0:15], v[198:201], v[190:193], v[0:15]
	ds_read_b128 v[190:193], v185 offset:23136
	s_waitcnt lgkmcnt(1)
	v_mfma_f32_32x32x16_bf16 v[48:63], v[202:205], v[186:189], v[48:63]
	s_waitcnt lgkmcnt(0)
	v_mfma_f32_32x32x16_bf16 v[16:31], v[202:205], v[190:193], v[16:31]
	v_mfma_f32_32x32x16_bf16 v[32:47], v[194:197], v[186:189], v[32:47]
	v_mfma_f32_32x32x16_bf16 v[0:15], v[194:197], v[190:193], v[0:15]
	s_setprio 0
	s_branch .Lj0_g3

; template <int BN>
; DI void gemm_main(f32x16 (&acc)[2][BN / 64], const GDesc& cur, const GDesc& nxt, GRegs<BN>& R, bool preloaded, char* smem) {
;     ...
;   for (int k0 = 0; k0 < K; k0 += 128) {
;     __syncthreads();
;     GM_STORE(R.ra0, R.rb0)
;     __syncthreads();
;     if (k0 + 128 < K) GM_LOAD(R.ra0, R.rb0, ap, wp, lda, ldw, k0 + 128)
;     else if (nxt.valid) GM_LOAD(R.ra0, R.rb0, apn, wpn, nxt.lda, nxt.ldw, 0)
;     GM_COMPUTE()
;     __syncthreads();
;     GM_STORE(R.ra1, R.rb1)
;     __syncthreads();
;     if (k0 + 192 < K) GM_LOAD(R.ra1, R.rb1, ap, wp, lda, ldw, k0 + 192)
;     else if (nxt.valid) GM_LOAD(R.ra1, R.rb1, apn, wpn, nxt.lda, nxt.ldw, 64)
;     GM_COMPUTE()
.Lj0_g3:
	s_cmp_ge_u32 s23, s4
	s_barrier
	s_waitcnt vmcnt(15)
	ds_write_b128 v136, v[68:71]
	s_waitcnt vmcnt(14)
	ds_write_b128 v136, v[76:79] offset:4608
	s_waitcnt vmcnt(13)
	ds_write_b128 v136, v[84:87] offset:9216
	s_waitcnt vmcnt(12)
	ds_write_b128 v136, v[92:95] offset:13824
	s_waitcnt vmcnt(11)
	ds_write_b128 v136, v[100:103] offset:18432
	s_waitcnt vmcnt(10)
	ds_write_b128 v136, v[108:111] offset:23040
	s_waitcnt vmcnt(9)
	ds_write_b128 v136, v[116:119] offset:27648
	s_waitcnt vmcnt(8)
	ds_write_b128 v136, v[124:127] offset:32256
	s_waitcnt lgkmcnt(0)
	s_barrier
	s_cbranch_scc1 .LBB0_536
	s_setprio 1
	ds_read_b128 v[206:209], v137
	ds_read_b128 v[210:213], v185 offset:23040
	ds_read_b128 v[214:217], v137 offset:4608
	ds_read_b128 v[218:221], v137 offset:32
	s_waitcnt lgkmcnt(2)
	v_mfma_f32_32x32x16_bf16 v[16:31], v[206:209], v[210:213], v[16:31]
	ds_read_b128 v[186:189], v185 offset:18432
	s_waitcnt lgkmcnt(0)
	v_mfma_f32_32x32x16_bf16 v[48:63], v[206:209], v[186:189], v[48:63]
	ds_read_b128 v[206:209], v185 offset:18464
	v_mfma_f32_32x32x16_bf16 v[32:47], v[214:217], v[186:189], v[32:47]
	ds_read_b128 v[186:189], v137 offset:4640
	global_load_dwordx4 v[68:71], v[152:153], off offset:384
	v_mfma_f32_32x32x16_bf16 v[0:15], v[214:217], v[210:213], v[0:15]
	ds_read_b128 v[210:213], v185 offset:23072
	global_load_dwordx4 v[76:79], v[154:155], off offset:384
	s_waitcnt lgkmcnt(2)
	v_mfma_f32_32x32x16_bf16 v[48:63], v[218:221], v[206:209], v[48:63]
	ds_read_b128 v[214:217], v137 offset:64
	global_load_dwordx4 v[84:87], v[156:157], off offset:384
	s_waitcnt lgkmcnt(1)
	v_mfma_f32_32x32x16_bf16 v[16:31], v[218:221], v[210:213], v[16:31]
	ds_read_b128 v[218:221], v137 offset:4672
	global_load_dwordx4 v[92:95], v[158:159], off offset:384
	v_mfma_f32_32x32x16_bf16 v[32:47], v[186:189], v[206:209], v[32:47]
	ds_read_b128 v[206:209], v185 offset:18496
	global_load_dwordx4 v[100:103], v[160:161], off offset:384
	v_mfma_f32_32x32x16_bf16 v[0:15], v[186:189], v[210:213], v[0:15]
	ds_read_b128 v[210:213], v185 offset:23104
	global_load_dwordx4 v[108:111], v[162:163], off offset:384
	s_waitcnt lgkmcnt(1)
	v_mfma_f32_32x32x16_bf16 v[48:63], v[214:217], v[206:209], v[48:63]
	ds_read_b128 v[186:189], v137 offset:96
	global_load_dwordx4 v[116:119], v[164:165], off offset:384
	s_waitcnt lgkmcnt(1)
	v_mfma_f32_32x32x16_bf16 v[16:31], v[214:217], v[210:213], v[16:31]
	ds_read_b128 v[214:217], v137 offset:4704
	global_load_dwordx4 v[124:127], v[166:167], off offset:384
	v_mfma_f32_32x32x16_bf16 v[32:47], v[218:221], v[206:209], v[32:47]
	ds_read_b128 v[206:209], v185 offset:18528
	v_mfma_f32_32x32x16_bf16 v[0:15], v[218:221], v[210:213], v[0:15]
	ds_read_b128 v[210:213], v185 offset:23136
	s_waitcnt lgkmcnt(1)
	v_mfma_f32_32x32x16_bf16 v[48:63], v[186:189], v[206:209], v[48:63]
	s_waitcnt lgkmcnt(0)
	v_mfma_f32_32x32x16_bf16 v[16:31], v[186:189], v[210:213], v[16:31]
	v_mfma_f32_32x32x16_bf16 v[32:47], v[214:217], v[206:209], v[32:47]
	v_mfma_f32_32x32x16_bf16 v[0:15], v[214:217], v[210:213], v[0:15]
	s_setprio 0
	s_branch .Lt1_g3

; template <int BN>
; DI void gemm_main(f32x16 (&acc)[2][BN / 64], const GDesc& cur, const GDesc& nxt, GRegs<BN>& R, bool preloaded, char* smem) {
;     ...
;   const u16* ap = cur.A + (size_t)(cur.m0 + (tid >> 3)) * cur.lda + (tid & 7) * 8;
;   const u16* wp = cur.W + (size_t)(cur.n0 + (tid >> 3)) * cur.ldw + (tid & 7) * 8;
;   const u16* apn = nxt.A + (size_t)(nxt.m0 + (tid >> 3)) * nxt.lda + (tid & 7) * 8;
;   const u16* wpn = nxt.W + (size_t)(nxt.n0 + (tid >> 3)) * nxt.ldw + (tid & 7) * 8;
;   const int lda = cur.lda, ldw = cur.ldw, K = cur.K;
;   u16* asw = As + (tid >> 3) * 72 + (tid & 7) * 8;
;   u16* bsw = Bs + (tid >> 3) * 72 + (tid & 7) * 8;
;     ...
;   if (!preloaded) {
;     GM_LOAD(R.ra0, R.rb0, ap, wp, lda, ldw, 0)
;     GM_LOAD(R.ra1, R.rb1, ap, wp, lda, ldw, 64)
; template <int NT>
; DI void zero_acc(f32x16 (&acc)[2][NT]) {
; #pragma unroll
;   for (int mi = 0; mi < 2; ++mi)
; #pragma unroll
;     for (int ni = 0; ni < NT; ++ni)
; #pragma unroll
;       for (int i = 0; i < 16; ++i) acc[mi][ni][i] = 0.f;
; }
.LBB0_952:
	s_and_b32 s4, s24, 7
	s_lshl_b32 s10, s4, 7
	s_ashr_i32 s4, s25, 31
	s_lshr_b32 s4, s4, 24
	s_add_i32 s4, s25, s4
	s_ashr_i32 s11, s4, 8
	s_and_b32 s4, s4, 0xffffff00
	s_sub_i32 s7, s25, s4
	s_lshl_b32 s4, s11, 3
	s_and_b32 s8, s25, 7
	s_or_b32 s4, s4, s8
	s_ashr_i32 s12, s7, 3
	v_mov_b32_e32 v16, v171
	s_bfe_u32 s6, s25, 0x30003
	s_and_b32 s7, s12, 0x1fffff8
	s_lshl_b32 s26, s4, 7
	s_lshl_b32 s9, s6, 7
	v_ashrrev_i32_e32 v17, 3, v16
	s_or_b32 s6, s7, s6
	v_add_u32_e32 v0, s26, v17
	s_lshl_b32 s27, s6, 7
	v_ashrrev_i32_e32 v1, 31, v0
	v_readlane_b32 s6, v251, 2
	v_lshlrev_b64 v[0:1], 11, v[0:1]
	v_readlane_b32 s7, v251, 3
	v_lshlrev_b32_e32 v2, 4, v16
	s_waitcnt vmcnt(0)
	v_and_b32_e32 v168, 0x70, v2
	v_lshl_add_u64 v[0:1], s[6:7], 0, v[0:1]
	v_lshl_add_u64 v[0:1], v[0:1], 0, v[168:169]
	s_mov_b32 s13, 0x10000
	v_add_co_u32_e32 v4, vcc, s13, v0
	v_add_u32_e32 v2, s27, v17
	s_nop 0
	v_addc_co_u32_e32 v5, vcc, 0, v1, vcc
	s_mov_b32 s14, 0x20000
	v_ashrrev_i32_e32 v3, 31, v2
	v_readlane_b32 s16, v254, 31
	v_add_co_u32_e32 v6, vcc, s14, v0
	v_lshlrev_b64 v[2:3], 11, v[2:3]
	v_readlane_b32 s17, v254, 32
	v_addc_co_u32_e32 v7, vcc, 0, v1, vcc
	s_mov_b32 s15, 0x30000
	v_lshl_add_u64 v[2:3], s[16:17], 0, v[2:3]
	v_add_co_u32_e32 v8, vcc, s15, v0
	v_lshl_add_u64 v[2:3], v[2:3], 0, v[168:169]
	s_nop 0
	v_addc_co_u32_e32 v9, vcc, 0, v1, vcc
	v_add_co_u32_e32 v10, vcc, s13, v2
	v_mad_u64_u32 v[128:129], s[6:7], v17, s53, v[168:169]
	s_nop 0
	v_addc_co_u32_e32 v11, vcc, 0, v3, vcc
	v_add_co_u32_e32 v12, vcc, s14, v2
	s_lshl_b32 s6, s12, 7
	s_nop 0
	v_addc_co_u32_e32 v13, vcc, 0, v3, vcc
	v_add_co_u32_e32 v14, vcc, s15, v2
	s_and_b32 s6, s6, 0xfffffc00
	s_nop 0
	v_addc_co_u32_e32 v15, vcc, 0, v3, vcc
	global_load_dwordx4 v[64:67], v[0:1], off
	global_load_dwordx4 v[72:75], v[4:5], off
	global_load_dwordx4 v[80:83], v[6:7], off
	global_load_dwordx4 v[88:91], v[8:9], off
	global_load_dwordx4 v[96:99], v[10:11], off
	global_load_dwordx4 v[104:107], v[12:13], off
	global_load_dwordx4 v[112:115], v[2:3], off
	global_load_dwordx4 v[120:123], v[14:15], off
	global_load_dwordx4 v[68:71], v[0:1], off offset:128
	global_load_dwordx4 v[76:79], v[4:5], off offset:128
	global_load_dwordx4 v[84:87], v[6:7], off offset:128
	global_load_dwordx4 v[92:95], v[8:9], off offset:128
	global_load_dwordx4 v[100:103], v[10:11], off offset:128
	global_load_dwordx4 v[108:111], v[12:13], off offset:128
	global_load_dwordx4 v[116:119], v[2:3], off offset:128
	global_load_dwordx4 v[124:127], v[14:15], off offset:128
	v_and_b32_e32 v0, 31, v16
	v_lshrrev_b32_e32 v1, 1, v16
	v_and_or_b32 v0, v1, s54, v0
	v_mul_lo_u32 v3, v0, s53
	v_and_b32_e32 v0, 7, v16
	s_or_b32 s6, s9, s6
	v_and_b32_e32 v2, 16, v1
	v_and_b32_e32 v1, 0x5f, v16
	v_lshlrev_b32_e32 v168, 4, v0
	v_add_u32_e32 v0, s6, v17
	v_mul_u32_u24_e32 v4, 0x90, v1
	v_ashrrev_i32_e32 v1, 31, v0
	s_lshl_b32 s6, s11, 10
	v_lshlrev_b64 v[0:1], 11, v[0:1]
	s_or_b32 s6, s10, s6
	v_lshl_add_u64 v[130:131], s[16:17], 0, v[0:1]
	v_add_u32_e32 v0, s6, v17
	v_ashrrev_i32_e32 v1, 31, v0
	v_lshlrev_b64 v[0:1], 11, v[0:1]
	v_lshl_add_u64 v[132:133], s[76:77], 0, v[0:1]
	v_mov_b32_e32 v0, 0
	s_mov_b32 s8, 0
	v_add_u32_e32 v129, v2, v3
	v_add_u32_e32 v138, v2, v4
	v_mov_b32_e32 v1, v0
	v_mov_b32_e32 v2, v0
	v_mov_b32_e32 v3, v0
	v_mov_b32_e32 v4, v0
	v_mov_b32_e32 v5, v0
	v_mov_b32_e32 v6, v0
	v_mov_b32_e32 v7, v0
	v_mov_b32_e32 v8, v0
	v_mov_b32_e32 v9, v0
	v_mov_b32_e32 v10, v0
	v_mov_b32_e32 v11, v0
	v_mov_b32_e32 v12, v0
	v_mov_b32_e32 v13, v0
	v_mov_b32_e32 v14, v0
	v_mov_b32_e32 v15, v0
	v_mov_b32_e32 v32, v0
	v_mov_b32_e32 v33, v0
	v_mov_b32_e32 v34, v0
	v_mov_b32_e32 v35, v0
	v_mov_b32_e32 v36, v0
	v_mov_b32_e32 v37, v0
	v_mov_b32_e32 v38, v0
	v_mov_b32_e32 v39, v0
	v_mov_b32_e32 v40, v0
	v_mov_b32_e32 v41, v0
	v_mov_b32_e32 v42, v0
	v_mov_b32_e32 v43, v0
	v_mov_b32_e32 v44, v0
	v_mov_b32_e32 v45, v0
	v_mov_b32_e32 v46, v0
	v_mov_b32_e32 v47, v0
	v_mov_b32_e32 v16, v0
	v_mov_b32_e32 v17, v0
	v_mov_b32_e32 v18, v0
	v_mov_b32_e32 v19, v0
	v_mov_b32_e32 v20, v0
	v_mov_b32_e32 v21, v0
	v_mov_b32_e32 v22, v0
	v_mov_b32_e32 v23, v0
	v_mov_b32_e32 v24, v0
	v_mov_b32_e32 v25, v0
	v_mov_b32_e32 v26, v0
	v_mov_b32_e32 v27, v0
	v_mov_b32_e32 v28, v0
	v_mov_b32_e32 v29, v0
	v_mov_b32_e32 v30, v0
	v_mov_b32_e32 v31, v0
	v_mov_b32_e32 v48, v0
	v_mov_b32_e32 v49, v0
	v_mov_b32_e32 v50, v0
	v_mov_b32_e32 v51, v0
	v_mov_b32_e32 v52, v0
	v_mov_b32_e32 v53, v0
	v_mov_b32_e32 v54, v0
	v_mov_b32_e32 v55, v0
	v_mov_b32_e32 v56, v0
	v_mov_b32_e32 v57, v0
	v_mov_b32_e32 v58, v0
	v_mov_b32_e32 v59, v0
	v_mov_b32_e32 v60, v0
	v_mov_b32_e32 v61, v0
	v_mov_b32_e32 v62, v0
	v_mov_b32_e32 v63, v0
	s_branch .LBB0_954

; template <int BN>
; DI void gemm_main(f32x16 (&acc)[2][BN / 64], const GDesc& cur, const GDesc& nxt, GRegs<BN>& R, bool preloaded, char* smem) {
;     ...
;   for (int k0 = 0; k0 < K; k0 += 128) {
;     __syncthreads();
;     GM_STORE(R.ra0, R.rb0)
;     __syncthreads();
;     if (k0 + 128 < K) GM_LOAD(R.ra0, R.rb0, ap, wp, lda, ldw, k0 + 128)
;     else if (nxt.valid) GM_LOAD(R.ra0, R.rb0, apn, wpn, nxt.lda, nxt.ldw, 0)
;     GM_COMPUTE()
;     __syncthreads();
;     GM_STORE(R.ra1, R.rb1)
;     __syncthreads();
;     if (k0 + 192 < K) GM_LOAD(R.ra1, R.rb1, ap, wp, lda, ldw, k0 + 192)
;     else if (nxt.valid) GM_LOAD(R.ra1, R.rb1, apn, wpn, nxt.lda, nxt.ldw, 64)
;     GM_COMPUTE()
.LBB0_954:
	s_cmpk_gt_u32 s8, 0x37f
	s_cselect_b64 s[6:7], -1, 0
	s_and_b64 vcc, exec, s[6:7]
	v_lshl_add_u64 v[136:137], v[132:133], 0, v[168:169]
	v_lshl_add_u64 v[134:135], v[130:131], 0, v[168:169]
	s_barrier
	s_waitcnt vmcnt(15)
	ds_write_b128 v128, v[64:67]
	s_waitcnt vmcnt(14)
	ds_write_b128 v128, v[72:75] offset:4608
	s_waitcnt vmcnt(13)
	ds_write_b128 v128, v[80:83] offset:9216
	s_waitcnt vmcnt(12)
	ds_write_b128 v128, v[88:91] offset:13824
	s_waitcnt vmcnt(9)
	ds_write_b128 v128, v[112:115] offset:18432
	s_waitcnt vmcnt(11)
	ds_write_b128 v128, v[96:99] offset:23040
	s_waitcnt vmcnt(10)
	ds_write_b128 v128, v[104:107] offset:27648
	s_waitcnt vmcnt(8)
	ds_write_b128 v128, v[120:123] offset:32256
	s_waitcnt lgkmcnt(0)
	s_barrier
	s_cbranch_vccnz .Lnopf_g4
	s_setprio 1
	ds_read_b128 v[140:143], v129
	ds_read_b128 v[144:147], v138 offset:23040
	ds_read_b128 v[148:151], v129 offset:4608
	ds_read_b128 v[152:155], v129 offset:32
	s_waitcnt lgkmcnt(2)
	v_mfma_f32_32x32x16_bf16 v[16:31], v[140:143], v[144:147], v[16:31]
	ds_read_b128 v[156:159], v138 offset:18432
	v_add_co_u32_e32 v64, vcc, 0x4110000, v136
	s_waitcnt lgkmcnt(0)
	v_mfma_f32_32x32x16_bf16 v[48:63], v[140:143], v[156:159], v[48:63]
	ds_read_b128 v[140:143], v138 offset:18464
	v_addc_co_u32_e32 v65, vcc, 0, v137, vcc
	v_add_co_u32_e32 v72, vcc, 0x4120000, v136
	v_mfma_f32_32x32x16_bf16 v[32:47], v[148:151], v[156:159], v[32:47]
	ds_read_b128 v[156:159], v129 offset:4640
	global_load_dwordx4 v[64:67], v[64:65], off offset:512
	v_addc_co_u32_e32 v73, vcc, 0, v137, vcc
	v_add_co_u32_e32 v80, vcc, 0x4130000, v136
	v_mfma_f32_32x32x16_bf16 v[0:15], v[148:151], v[144:147], v[0:15]
	ds_read_b128 v[144:147], v138 offset:23072
	global_load_dwordx4 v[72:75], v[72:73], off offset:512
	v_addc_co_u32_e32 v81, vcc, 0, v137, vcc
	v_add_co_u32_e32 v88, vcc, 0x4140000, v136
	s_waitcnt lgkmcnt(2)
	v_mfma_f32_32x32x16_bf16 v[48:63], v[152:155], v[140:143], v[48:63]
	ds_read_b128 v[148:151], v129 offset:64
	global_load_dwordx4 v[80:83], v[80:81], off offset:512
	v_addc_co_u32_e32 v89, vcc, 0, v137, vcc
	v_add_co_u32_e32 v96, vcc, 0x10000, v134
	s_waitcnt lgkmcnt(1)
	v_mfma_f32_32x32x16_bf16 v[16:31], v[152:155], v[144:147], v[16:31]
	ds_read_b128 v[152:155], v129 offset:4672
	global_load_dwordx4 v[88:91], v[88:89], off offset:512
	v_addc_co_u32_e32 v97, vcc, 0, v135, vcc
	v_add_co_u32_e32 v104, vcc, 0x20000, v134
	v_mfma_f32_32x32x16_bf16 v[32:47], v[156:159], v[140:143], v[32:47]
	ds_read_b128 v[140:143], v138 offset:18496
	global_load_dwordx4 v[96:99], v[96:97], off offset:256
	v_addc_co_u32_e32 v105, vcc, 0, v135, vcc
	v_mfma_f32_32x32x16_bf16 v[0:15], v[156:159], v[144:147], v[0:15]
	ds_read_b128 v[144:147], v138 offset:23104
	global_load_dwordx4 v[104:107], v[104:105], off offset:256
	v_add_co_u32_e32 v120, vcc, 0x30000, v134
	s_waitcnt lgkmcnt(1)
	v_mfma_f32_32x32x16_bf16 v[48:63], v[148:151], v[140:143], v[48:63]
	ds_read_b128 v[156:159], v129 offset:96
	global_load_dwordx4 v[112:115], v[134:135], off offset:256
	v_addc_co_u32_e32 v121, vcc, 0, v135, vcc
	s_waitcnt lgkmcnt(1)
	v_mfma_f32_32x32x16_bf16 v[16:31], v[148:151], v[144:147], v[16:31]
	ds_read_b128 v[148:151], v129 offset:4704
	global_load_dwordx4 v[120:123], v[120:121], off offset:256
	v_mfma_f32_32x32x16_bf16 v[32:47], v[152:155], v[140:143], v[32:47]
	ds_read_b128 v[140:143], v138 offset:18528
	v_mfma_f32_32x32x16_bf16 v[0:15], v[152:155], v[144:147], v[0:15]
	ds_read_b128 v[144:147], v138 offset:23136
	s_waitcnt lgkmcnt(1)
	v_mfma_f32_32x32x16_bf16 v[48:63], v[156:159], v[140:143], v[48:63]
	s_waitcnt lgkmcnt(0)
	v_mfma_f32_32x32x16_bf16 v[16:31], v[156:159], v[144:147], v[16:31]
	v_mfma_f32_32x32x16_bf16 v[32:47], v[148:151], v[140:143], v[32:47]
	v_mfma_f32_32x32x16_bf16 v[0:15], v[148:151], v[144:147], v[0:15]
	s_setprio 0
	s_branch .Lj0_g4

; template <int BN>
; DI void gemm_main(f32x16 (&acc)[2][BN / 64], const GDesc& cur, const GDesc& nxt, GRegs<BN>& R, bool preloaded, char* smem) {
;     ...
;   for (int k0 = 0; k0 < K; k0 += 128) {
;     __syncthreads();
;     GM_STORE(R.ra0, R.rb0)
;     __syncthreads();
;     if (k0 + 128 < K) GM_LOAD(R.ra0, R.rb0, ap, wp, lda, ldw, k0 + 128)
;     else if (nxt.valid) GM_LOAD(R.ra0, R.rb0, apn, wpn, nxt.lda, nxt.ldw, 0)
;     GM_COMPUTE()
;     __syncthreads();
;     GM_STORE(R.ra1, R.rb1)
;     __syncthreads();
;     if (k0 + 192 < K) GM_LOAD(R.ra1, R.rb1, ap, wp, lda, ldw, k0 + 192)
;     else if (nxt.valid) GM_LOAD(R.ra1, R.rb1, apn, wpn, nxt.lda, nxt.ldw, 64)
;     GM_COMPUTE()
.Lj0_g4:
	s_cmpk_gt_u32 s8, 0x33f
	s_barrier
	s_waitcnt vmcnt(15)
	ds_write_b128 v128, v[68:71]
	s_waitcnt vmcnt(14)
	ds_write_b128 v128, v[76:79] offset:4608
	s_waitcnt vmcnt(13)
	ds_write_b128 v128, v[84:87] offset:9216
	s_waitcnt vmcnt(12)
	ds_write_b128 v128, v[92:95] offset:13824
	s_waitcnt vmcnt(9)
	ds_write_b128 v128, v[116:119] offset:18432
	s_waitcnt vmcnt(11)
	ds_write_b128 v128, v[100:103] offset:23040
	s_waitcnt vmcnt(10)
	ds_write_b128 v128, v[108:111] offset:27648
	s_waitcnt vmcnt(8)
	ds_write_b128 v128, v[124:127] offset:32256
	s_waitcnt lgkmcnt(0)
	s_barrier
	s_cbranch_scc1 .LBB0_953
	s_addk_i32 s8, 0x80
	s_setprio 1
	ds_read_b128 v[160:163], v129
	ds_read_b128 v[140:143], v138 offset:23040
	ds_read_b128 v[144:147], v129 offset:4608
	ds_read_b128 v[148:151], v129 offset:32
	s_waitcnt lgkmcnt(2)
	v_mfma_f32_32x32x16_bf16 v[16:31], v[160:163], v[140:143], v[16:31]
	ds_read_b128 v[152:155], v138 offset:18432
	v_add_co_u32_e32 v68, vcc, 0x4110000, v136
	s_waitcnt lgkmcnt(0)
	v_mfma_f32_32x32x16_bf16 v[48:63], v[160:163], v[152:155], v[48:63]
	ds_read_b128 v[160:163], v138 offset:18464
	v_addc_co_u32_e32 v69, vcc, 0, v137, vcc
	v_add_co_u32_e32 v76, vcc, 0x4120000, v136
	v_mfma_f32_32x32x16_bf16 v[32:47], v[144:147], v[152:155], v[32:47]
	ds_read_b128 v[152:155], v129 offset:4640
	global_load_dwordx4 v[68:71], v[68:69], off offset:640
	v_addc_co_u32_e32 v77, vcc, 0, v137, vcc
	v_add_co_u32_e32 v84, vcc, 0x4130000, v136
	v_mfma_f32_32x32x16_bf16 v[0:15], v[144:147], v[140:143], v[0:15]
	ds_read_b128 v[140:143], v138 offset:23072
	global_load_dwordx4 v[76:79], v[76:77], off offset:640
	v_addc_co_u32_e32 v85, vcc, 0, v137, vcc
	v_add_co_u32_e32 v92, vcc, 0x4140000, v136
	s_waitcnt lgkmcnt(2)
	v_mfma_f32_32x32x16_bf16 v[48:63], v[148:151], v[160:163], v[48:63]
	ds_read_b128 v[144:147], v129 offset:64
	global_load_dwordx4 v[84:87], v[84:85], off offset:640
	v_addc_co_u32_e32 v93, vcc, 0, v137, vcc
	v_add_co_u32_e32 v100, vcc, 0x10000, v134
	s_waitcnt lgkmcnt(1)
	v_mfma_f32_32x32x16_bf16 v[16:31], v[148:151], v[140:143], v[16:31]
	ds_read_b128 v[148:151], v129 offset:4672
	global_load_dwordx4 v[92:95], v[92:93], off offset:640
	v_addc_co_u32_e32 v101, vcc, 0, v135, vcc
	v_add_co_u32_e32 v108, vcc, 0x20000, v134
	v_mfma_f32_32x32x16_bf16 v[32:47], v[152:155], v[160:163], v[32:47]
	ds_read_b128 v[160:163], v138 offset:18496
	global_load_dwordx4 v[100:103], v[100:101], off offset:384
	v_addc_co_u32_e32 v109, vcc, 0, v135, vcc
	v_mfma_f32_32x32x16_bf16 v[0:15], v[152:155], v[140:143], v[0:15]
	ds_read_b128 v[140:143], v138 offset:23104
	global_load_dwordx4 v[108:111], v[108:109], off offset:384
	v_add_co_u32_e32 v124, vcc, 0x30000, v134
	s_waitcnt lgkmcnt(1)
	v_mfma_f32_32x32x16_bf16 v[48:63], v[144:147], v[160:163], v[48:63]
	ds_read_b128 v[152:155], v129 offset:96
	global_load_dwordx4 v[116:119], v[134:135], off offset:384
	v_addc_co_u32_e32 v125, vcc, 0, v135, vcc
	s_waitcnt lgkmcnt(1)
	v_mfma_f32_32x32x16_bf16 v[16:31], v[144:147], v[140:143], v[16:31]
	ds_read_b128 v[144:147], v129 offset:4704
	global_load_dwordx4 v[124:127], v[124:125], off offset:384
	v_mfma_f32_32x32x16_bf16 v[32:47], v[148:151], v[160:163], v[32:47]
	ds_read_b128 v[160:163], v138 offset:18528
	v_mfma_f32_32x32x16_bf16 v[0:15], v[148:151], v[140:143], v[0:15]
	ds_read_b128 v[140:143], v138 offset:23136
	s_waitcnt lgkmcnt(1)
	v_mfma_f32_32x32x16_bf16 v[48:63], v[152:155], v[160:163], v[48:63]
	s_waitcnt lgkmcnt(0)
	v_mfma_f32_32x32x16_bf16 v[16:31], v[152:155], v[140:143], v[16:31]
	v_mfma_f32_32x32x16_bf16 v[32:47], v[144:147], v[160:163], v[32:47]
	v_mfma_f32_32x32x16_bf16 v[0:15], v[144:147], v[140:143], v[0:15]
	s_setprio 0
	s_branch .Lt1_g4
